# GEMM main loops: the redundant s_waitcnt lgkmcnt(0) after each phase barrier removed (the one before the barrier already drained the reads)
# baseline (speedup 1.0000x reference)
; #define PG8_STAGE(bufoff, gbase, voff) do { _Pragma("unroll") for (int _i = 0; _i < 2; ++_i) \
;         __builtin_amdgcn_global_load_lds((const unsigned*)((const char*)(gbase) + (voff)[_i]), (LAS unsigned*)(lds + (bufoff) + ldsw + _i * 8192), 16, 0, 0); } while (0)
; #define PG8_LDA(dst, b, h) do { _Pragma("unroll") for (int m = 0; m < 4; ++m) _Pragma("unroll") for (int k = 0; k < 2; ++k) dst[m][k] = *(const LAS bf16x8*)(lds + PG8_SA(b, h) + aoff + m * 2048 + k * 1024); } while (0)
; #define PG8_LDB(dst, b, h) do { _Pragma("unroll") for (int n = 0; n < 2; ++n) _Pragma("unroll") for (int k = 0; k < 2; ++k) dst[n][k] = *(const LAS bf16x8*)(lds + PG8_SB(b, h) + boff + n * 2048 + k * 1024); } while (0)
; #define PG8_MMA(ai, bj, At, Bt) do { __builtin_amdgcn_s_setprio(1); _Pragma("unroll") for (int m = 0; m < 4; ++m) _Pragma("unroll") for (int n = 0; n < 2; ++n) _Pragma("unroll") for (int k = 0; k < 2; ++k) \
;         acc[ai][bj][m][n] = __builtin_amdgcn_mfma_f32_16x16x32_bf16(Bt[n][k], At[m][k], acc[ai][bj][m][n], 0, 0, 0); __builtin_amdgcn_s_setprio(0); } while (0)
; #define PG8_WAIT_V(n) asm volatile("s_waitcnt vmcnt(" #n ")" ::: "memory")
; #define PG8_WAIT_L(n) asm volatile("s_waitcnt lgkmcnt(" #n ")" ::: "memory")
; #define PG8_BAR __builtin_amdgcn_s_barrier()
; #define PG8_SCHED __builtin_amdgcn_sched_barrier(0)
; template <class Epi, class Sched, bool ALIGN_EPI>
; DI void gemm_phase(LAS unsigned char* lds, const Gemm g, const Sched& S, const Epi& E) {
;     ...
;             const bool last = (t == nt - 2);
;             const char* a1 = cA + (size_t)(t + 1) * kstep;
;             const char* a2 = last ? nA : cA + (size_t)(t + 2) * kstep; const char* b2 = last ? nB : cB + (size_t)(t + 2) * kstep;
;             const char* a3 = a2 + kstep; const char* b3 = b2 + kstep;
;             PG8_LDB(B0, 0, 0); PG8_LDB(B1, 0, 1); PG8_SCHED; PG8_LDA(At, 0, 0); PG8_STAGE(PG8_SA(1, 1), a1 + hstep, voffA);
;             PG8_WAIT_V(8); PG8_WAIT_L(0); PG8_BAR; PG8_MMA(0, 0, At, B0); PG8_MMA(0, 1, At, B1); PG8_BAR; PG8_SCHED;
;             PG8_LDA(At, 0, 1); PG8_STAGE(PG8_SB(0, 0), b2, voffA); PG8_STAGE(PG8_SB(0, 1), b2 + hstep, voffA); PG8_STAGE(PG8_SA(0, 0), a2, voffA);
;             PG8_WAIT_V(8); PG8_WAIT_L(0); PG8_BAR; PG8_MMA(1, 0, At, B0); PG8_MMA(1, 1, At, B1); PG8_BAR; PG8_SCHED;
.LBB0_104:
	ds_read_b128 v[48:51], v196
	ds_read_b128 v[52:55], v196 offset:1024
	ds_read_b128 v[56:59], v196 offset:2048
	ds_read_b128 v[60:63], v196 offset:3072
	ds_read_b128 v[182:185], v197
	ds_read_b128 v[186:189], v197 offset:1024
	ds_read_b128 v[200:203], v197 offset:2048
	ds_read_b128 v[204:207], v197 offset:3072
	s_add_u32 s8, s0, 0xfffc0080
	s_addc_u32 s9, s1, -1
	s_cmp_eq_u32 s47, 12
	s_cselect_b32 s45, s7, s9
	s_cselect_b32 s44, s11, s8
	s_cselect_b32 s9, s18, s46
	s_cselect_b32 s8, s29, s31
	s_add_i32 m0, s64, 0xc000
	ds_read_b128 v[208:211], v194
	ds_read_b128 v[212:215], v194 offset:1024
	ds_read_b128 v[216:219], v194 offset:2048
	ds_read_b128 v[220:223], v194 offset:3072
	ds_read_b128 v[228:231], v194 offset:4096
	ds_read_b128 v[232:235], v194 offset:5120
	ds_read_b128 v[236:239], v194 offset:6144
	ds_read_b128 v[240:243], v194 offset:7168
	global_load_lds_dwordx4 v174, s[0:1]
	s_add_i32 m0, s64, 0xe000
	s_nop 0
	global_load_lds_dwordx4 v176, s[0:1]
	s_waitcnt vmcnt(8)
	s_waitcnt lgkmcnt(0)
	s_barrier
	v_mfma_f32_16x16x32_bf16 v[140:143], v[48:51], v[208:211], v[140:143]
	v_mfma_f32_16x16x32_bf16 v[136:139], v[56:59], v[208:211], v[136:139]
	v_mfma_f32_16x16x32_bf16 v[124:127], v[48:51], v[216:219], v[124:127]
	v_mfma_f32_16x16x32_bf16 v[120:123], v[56:59], v[216:219], v[120:123]
	v_mfma_f32_16x16x32_bf16 v[108:111], v[48:51], v[228:231], v[108:111]
	v_mfma_f32_16x16x32_bf16 v[104:107], v[56:59], v[228:231], v[104:107]
	v_mfma_f32_16x16x32_bf16 v[92:95], v[48:51], v[236:239], v[92:95]
	v_mfma_f32_16x16x32_bf16 v[88:91], v[56:59], v[236:239], v[88:91]
	v_mfma_f32_16x16x32_bf16 v[140:143], v[52:55], v[212:215], v[140:143]
	v_mfma_f32_16x16x32_bf16 v[136:139], v[60:63], v[212:215], v[136:139]
	v_mfma_f32_16x16x32_bf16 v[124:127], v[52:55], v[220:223], v[124:127]
	v_mfma_f32_16x16x32_bf16 v[120:123], v[60:63], v[220:223], v[120:123]
	v_mfma_f32_16x16x32_bf16 v[108:111], v[52:55], v[232:235], v[108:111]
	v_mfma_f32_16x16x32_bf16 v[104:107], v[60:63], v[232:235], v[104:107]
	v_mfma_f32_16x16x32_bf16 v[92:95], v[52:55], v[240:243], v[92:95]
	v_mfma_f32_16x16x32_bf16 v[88:91], v[60:63], v[240:243], v[88:91]
	v_mfma_f32_16x16x32_bf16 v[132:135], v[182:185], v[208:211], v[132:135]
	v_mfma_f32_16x16x32_bf16 v[128:131], v[200:203], v[208:211], v[128:131]
	v_mfma_f32_16x16x32_bf16 v[116:119], v[182:185], v[216:219], v[116:119]
	v_mfma_f32_16x16x32_bf16 v[112:115], v[200:203], v[216:219], v[112:115]
	v_mfma_f32_16x16x32_bf16 v[100:103], v[182:185], v[228:231], v[100:103]
	v_mfma_f32_16x16x32_bf16 v[96:99], v[200:203], v[228:231], v[96:99]
	v_mfma_f32_16x16x32_bf16 v[84:87], v[182:185], v[236:239], v[84:87]
	v_mfma_f32_16x16x32_bf16 v[80:83], v[200:203], v[236:239], v[80:83]
	v_mfma_f32_16x16x32_bf16 v[132:135], v[186:189], v[212:215], v[132:135]
	v_mfma_f32_16x16x32_bf16 v[128:131], v[204:207], v[212:215], v[128:131]
	v_mfma_f32_16x16x32_bf16 v[116:119], v[186:189], v[220:223], v[116:119]
	v_mfma_f32_16x16x32_bf16 v[112:115], v[204:207], v[220:223], v[112:115]
	v_mfma_f32_16x16x32_bf16 v[100:103], v[186:189], v[232:235], v[100:103]
	v_mfma_f32_16x16x32_bf16 v[96:99], v[204:207], v[232:235], v[96:99]
	v_mfma_f32_16x16x32_bf16 v[84:87], v[186:189], v[240:243], v[84:87]
	v_mfma_f32_16x16x32_bf16 v[80:83], v[204:207], v[240:243], v[80:83]
	s_barrier
	s_add_i32 s48, s75, s63
	s_add_u32 s94, s8, s22
	s_addc_u32 s95, s9, s23
	s_add_u32 s96, s44, s22
	s_addc_u32 s97, s45, s23
	s_mov_b32 m0, s48
	ds_read_b128 v[208:211], v194 offset:16384
	ds_read_b128 v[212:215], v194 offset:17408
	ds_read_b128 v[216:219], v194 offset:18432
	ds_read_b128 v[220:223], v194 offset:19456
	ds_read_b128 v[228:231], v194 offset:20480
	ds_read_b128 v[232:235], v194 offset:21504
	ds_read_b128 v[236:239], v194 offset:22528
	ds_read_b128 v[240:243], v194 offset:23552
	global_load_lds_dwordx4 v146, s[8:9]
	s_add_i32 m0, s48, 0x2000
	s_add_u32 s48, s8, 0x40000
	s_addc_u32 s49, s9, 0
	s_add_i32 s50, s76, s63
	global_load_lds_dwordx4 v148, s[8:9]
	s_mov_b32 m0, s50
	s_nop 0
	global_load_lds_dwordx4 v146, s[48:49]
	s_add_i32 m0, s50, 0x2000
	s_nop 0
	global_load_lds_dwordx4 v148, s[48:49]
	s_mov_b32 m0, s64
	s_nop 0
	global_load_lds_dwordx4 v146, s[44:45]
	s_mov_b32 m0, s65
	s_nop 0
	global_load_lds_dwordx4 v148, s[44:45]
	s_waitcnt vmcnt(8)
	s_waitcnt lgkmcnt(0)
	s_barrier
	v_mfma_f32_16x16x32_bf16 v[76:79], v[48:51], v[208:211], v[76:79]
	v_mfma_f32_16x16x32_bf16 v[72:75], v[56:59], v[208:211], v[72:75]
	v_mfma_f32_16x16x32_bf16 v[44:47], v[48:51], v[216:219], v[44:47]
	v_mfma_f32_16x16x32_bf16 v[40:43], v[56:59], v[216:219], v[40:43]
	v_mfma_f32_16x16x32_bf16 v[28:31], v[48:51], v[228:231], v[28:31]
	v_mfma_f32_16x16x32_bf16 v[24:27], v[56:59], v[228:231], v[24:27]
	v_mfma_f32_16x16x32_bf16 v[12:15], v[48:51], v[236:239], v[12:15]
	v_mfma_f32_16x16x32_bf16 v[8:11], v[56:59], v[236:239], v[8:11]
	v_mfma_f32_16x16x32_bf16 v[76:79], v[52:55], v[212:215], v[76:79]
	v_mfma_f32_16x16x32_bf16 v[72:75], v[60:63], v[212:215], v[72:75]
	v_mfma_f32_16x16x32_bf16 v[44:47], v[52:55], v[220:223], v[44:47]
	v_mfma_f32_16x16x32_bf16 v[40:43], v[60:63], v[220:223], v[40:43]
	v_mfma_f32_16x16x32_bf16 v[28:31], v[52:55], v[232:235], v[28:31]
	v_mfma_f32_16x16x32_bf16 v[24:27], v[60:63], v[232:235], v[24:27]
	v_mfma_f32_16x16x32_bf16 v[12:15], v[52:55], v[240:243], v[12:15]
	v_mfma_f32_16x16x32_bf16 v[8:11], v[60:63], v[240:243], v[8:11]
	v_mfma_f32_16x16x32_bf16 v[36:39], v[182:185], v[216:219], v[36:39]
	v_mfma_f32_16x16x32_bf16 v[32:35], v[200:203], v[216:219], v[32:35]
	v_mfma_f32_16x16x32_bf16 v[20:23], v[182:185], v[228:231], v[20:23]
	v_mfma_f32_16x16x32_bf16 v[16:19], v[200:203], v[228:231], v[16:19]
	v_mfma_f32_16x16x32_bf16 v[4:7], v[182:185], v[236:239], v[4:7]
	v_mfma_f32_16x16x32_bf16 v[0:3], v[200:203], v[236:239], v[0:3]
	v_mfma_f32_16x16x32_bf16 v[48:51], v[182:185], v[208:211], v[68:71]
	v_mfma_f32_16x16x32_bf16 v[52:55], v[200:203], v[208:211], v[64:67]
	v_mfma_f32_16x16x32_bf16 v[36:39], v[186:189], v[220:223], v[36:39]
	v_mfma_f32_16x16x32_bf16 v[32:35], v[204:207], v[220:223], v[32:35]
	v_mfma_f32_16x16x32_bf16 v[20:23], v[186:189], v[232:235], v[20:23]
	v_mfma_f32_16x16x32_bf16 v[16:19], v[204:207], v[232:235], v[16:19]
	v_mfma_f32_16x16x32_bf16 v[4:7], v[186:189], v[240:243], v[4:7]
	v_mfma_f32_16x16x32_bf16 v[0:3], v[204:207], v[240:243], v[0:3]
	v_mfma_f32_16x16x32_bf16 v[48:51], v[186:189], v[212:215], v[48:51]
	v_mfma_f32_16x16x32_bf16 v[52:55], v[204:207], v[212:215], v[52:55]
	s_barrier
; #define PG8_STAGE(bufoff, gbase, voff) do { _Pragma("unroll") for (int _i = 0; _i < 2; ++_i) \
;         __builtin_amdgcn_global_load_lds((const unsigned*)((const char*)(gbase) + (voff)[_i]), (LAS unsigned*)(lds + (bufoff) + ldsw + _i * 8192), 16, 0, 0); } while (0)
; #define PG8_LDA(dst, b, h) do { _Pragma("unroll") for (int m = 0; m < 4; ++m) _Pragma("unroll") for (int k = 0; k < 2; ++k) dst[m][k] = *(const LAS bf16x8*)(lds + PG8_SA(b, h) + aoff + m * 2048 + k * 1024); } while (0)
; #define PG8_LDB(dst, b, h) do { _Pragma("unroll") for (int n = 0; n < 2; ++n) _Pragma("unroll") for (int k = 0; k < 2; ++k) dst[n][k] = *(const LAS bf16x8*)(lds + PG8_SB(b, h) + boff + n * 2048 + k * 1024); } while (0)
; #define PG8_MMA(ai, bj, At, Bt) do { __builtin_amdgcn_s_setprio(1); _Pragma("unroll") for (int m = 0; m < 4; ++m) _Pragma("unroll") for (int n = 0; n < 2; ++n) _Pragma("unroll") for (int k = 0; k < 2; ++k) \
;         acc[ai][bj][m][n] = __builtin_amdgcn_mfma_f32_16x16x32_bf16(Bt[n][k], At[m][k], acc[ai][bj][m][n], 0, 0, 0); __builtin_amdgcn_s_setprio(0); } while (0)
; #define PG8_WAIT_V(n) asm volatile("s_waitcnt vmcnt(" #n ")" ::: "memory")
; #define PG8_WAIT_L(n) asm volatile("s_waitcnt lgkmcnt(" #n ")" ::: "memory")
; #define PG8_BAR __builtin_amdgcn_s_barrier()
; #define PG8_SCHED __builtin_amdgcn_sched_barrier(0)
; template <class Epi, class Sched, bool ALIGN_EPI>
; DI void gemm_phase(LAS unsigned char* lds, const Gemm g, const Sched& S, const Epi& E) {
;     ...
;             PG8_LDB(B0, 1, 0); PG8_LDB(B1, 1, 1); PG8_SCHED; PG8_LDA(At, 1, 0); PG8_STAGE(PG8_SA(0, 1), a2 + hstep, voffA);
;             PG8_WAIT_V(8); PG8_WAIT_L(0); PG8_BAR; PG8_MMA(0, 0, At, B0); PG8_MMA(0, 1, At, B1); PG8_BAR; PG8_SCHED;
;             PG8_LDA(At, 1, 1); PG8_STAGE(PG8_SB(1, 0), b3, voffA); PG8_STAGE(PG8_SB(1, 1), b3 + hstep, voffA); PG8_STAGE(PG8_SA(1, 0), a3, voffA);
;             PG8_WAIT_V(8); PG8_WAIT_L(0); PG8_BAR; PG8_MMA(1, 0, At, B0); PG8_MMA(1, 1, At, B1); PG8_BAR; PG8_SCHED;
;         }
	s_add_i32 s48, 0, 0x18000
	s_add_i32 s49, 0, 0x1c000
	v_add_u32_e32 v68, s48, v157
	v_add_u32_e32 v150, s49, v157
	ds_read_b128 v[56:59], v68
	ds_read_b128 v[60:63], v68 offset:1024
	ds_read_b128 v[64:67], v68 offset:2048
	ds_read_b128 v[68:71], v68 offset:3072
	ds_read_b128 v[182:185], v150
	ds_read_b128 v[186:189], v150 offset:1024
	ds_read_b128 v[200:203], v150 offset:2048
	ds_read_b128 v[204:207], v150 offset:3072
	s_add_u32 s44, s44, 0x40000
	s_addc_u32 s45, s45, 0
	s_mov_b32 m0, s66
	ds_read_b128 v[208:211], v194 offset:32768
	ds_read_b128 v[212:215], v194 offset:33792
	ds_read_b128 v[216:219], v194 offset:34816
	ds_read_b128 v[220:223], v194 offset:35840
	ds_read_b128 v[228:231], v194 offset:36864
	ds_read_b128 v[232:235], v194 offset:37888
	ds_read_b128 v[236:239], v194 offset:38912
	ds_read_b128 v[240:243], v194 offset:39936
	global_load_lds_dwordx4 v146, s[44:45]
	s_mov_b32 m0, s67
	s_nop 0
	global_load_lds_dwordx4 v148, s[44:45]
	s_waitcnt vmcnt(8)
	s_waitcnt lgkmcnt(0)
	s_barrier
	v_mfma_f32_16x16x32_bf16 v[140:143], v[56:59], v[208:211], v[140:143]
	v_mfma_f32_16x16x32_bf16 v[136:139], v[64:67], v[208:211], v[136:139]
	v_mfma_f32_16x16x32_bf16 v[124:127], v[56:59], v[216:219], v[124:127]
	v_mfma_f32_16x16x32_bf16 v[120:123], v[64:67], v[216:219], v[120:123]
	v_mfma_f32_16x16x32_bf16 v[108:111], v[56:59], v[228:231], v[108:111]
	v_mfma_f32_16x16x32_bf16 v[104:107], v[64:67], v[228:231], v[104:107]
	v_mfma_f32_16x16x32_bf16 v[92:95], v[56:59], v[236:239], v[92:95]
	v_mfma_f32_16x16x32_bf16 v[88:91], v[64:67], v[236:239], v[88:91]
	v_mfma_f32_16x16x32_bf16 v[140:143], v[60:63], v[212:215], v[140:143]
	v_mfma_f32_16x16x32_bf16 v[136:139], v[68:71], v[212:215], v[136:139]
	v_mfma_f32_16x16x32_bf16 v[124:127], v[60:63], v[220:223], v[124:127]
	v_mfma_f32_16x16x32_bf16 v[120:123], v[68:71], v[220:223], v[120:123]
	v_mfma_f32_16x16x32_bf16 v[108:111], v[60:63], v[232:235], v[108:111]
	v_mfma_f32_16x16x32_bf16 v[104:107], v[68:71], v[232:235], v[104:107]
	v_mfma_f32_16x16x32_bf16 v[92:95], v[60:63], v[240:243], v[92:95]
	v_mfma_f32_16x16x32_bf16 v[88:91], v[68:71], v[240:243], v[88:91]
	v_mfma_f32_16x16x32_bf16 v[132:135], v[182:185], v[208:211], v[132:135]
	v_mfma_f32_16x16x32_bf16 v[128:131], v[200:203], v[208:211], v[128:131]
	v_mfma_f32_16x16x32_bf16 v[116:119], v[182:185], v[216:219], v[116:119]
	v_mfma_f32_16x16x32_bf16 v[112:115], v[200:203], v[216:219], v[112:115]
	v_mfma_f32_16x16x32_bf16 v[100:103], v[182:185], v[228:231], v[100:103]
	v_mfma_f32_16x16x32_bf16 v[96:99], v[200:203], v[228:231], v[96:99]
	v_mfma_f32_16x16x32_bf16 v[84:87], v[182:185], v[236:239], v[84:87]
	v_mfma_f32_16x16x32_bf16 v[80:83], v[200:203], v[236:239], v[80:83]
	v_mfma_f32_16x16x32_bf16 v[132:135], v[186:189], v[212:215], v[132:135]
	v_mfma_f32_16x16x32_bf16 v[128:131], v[204:207], v[212:215], v[128:131]
	v_mfma_f32_16x16x32_bf16 v[116:119], v[186:189], v[220:223], v[116:119]
	v_mfma_f32_16x16x32_bf16 v[112:115], v[204:207], v[220:223], v[112:115]
	v_mfma_f32_16x16x32_bf16 v[100:103], v[186:189], v[232:235], v[100:103]
	v_mfma_f32_16x16x32_bf16 v[96:99], v[204:207], v[232:235], v[96:99]
	v_mfma_f32_16x16x32_bf16 v[84:87], v[186:189], v[240:243], v[84:87]
	v_mfma_f32_16x16x32_bf16 v[80:83], v[204:207], v[240:243], v[80:83]
	s_barrier
	s_add_i32 s44, s48, s63
	s_mov_b32 m0, s44
	ds_read_b128 v[208:211], v194 offset:49152
	ds_read_b128 v[212:215], v194 offset:50176
	ds_read_b128 v[216:219], v194 offset:51200
	ds_read_b128 v[220:223], v194 offset:52224
	ds_read_b128 v[228:231], v194 offset:53248
	ds_read_b128 v[232:235], v194 offset:54272
	ds_read_b128 v[236:239], v194 offset:55296
	ds_read_b128 v[240:243], v194 offset:56320
	global_load_lds_dwordx4 v146, s[94:95]
	s_add_i32 m0, s44, 0x2000
	s_add_u32 s8, s8, 0x40080
	s_addc_u32 s9, s9, 0
	s_add_i32 s44, s49, s63
	global_load_lds_dwordx4 v148, s[94:95]
	s_mov_b32 m0, s44
	s_nop 0
	global_load_lds_dwordx4 v146, s[8:9]
	s_add_i32 m0, s44, 0x2000
	s_nop 0
	global_load_lds_dwordx4 v148, s[8:9]
	s_mov_b32 m0, s70
	s_nop 0
	global_load_lds_dwordx4 v146, s[96:97]
	s_mov_b32 m0, s71
	s_nop 0
	global_load_lds_dwordx4 v148, s[96:97]
	s_waitcnt vmcnt(8)
	s_waitcnt lgkmcnt(0)
	s_barrier
	v_mfma_f32_16x16x32_bf16 v[76:79], v[56:59], v[208:211], v[76:79]
	v_mfma_f32_16x16x32_bf16 v[72:75], v[64:67], v[208:211], v[72:75]
	v_mfma_f32_16x16x32_bf16 v[44:47], v[56:59], v[216:219], v[44:47]
	v_mfma_f32_16x16x32_bf16 v[40:43], v[64:67], v[216:219], v[40:43]
	v_mfma_f32_16x16x32_bf16 v[28:31], v[56:59], v[228:231], v[28:31]
	v_mfma_f32_16x16x32_bf16 v[24:27], v[64:67], v[228:231], v[24:27]
	v_mfma_f32_16x16x32_bf16 v[12:15], v[56:59], v[236:239], v[12:15]
	v_mfma_f32_16x16x32_bf16 v[8:11], v[64:67], v[236:239], v[8:11]
	v_mfma_f32_16x16x32_bf16 v[76:79], v[60:63], v[212:215], v[76:79]
	v_mfma_f32_16x16x32_bf16 v[72:75], v[68:71], v[212:215], v[72:75]
	v_mfma_f32_16x16x32_bf16 v[44:47], v[60:63], v[220:223], v[44:47]
	v_mfma_f32_16x16x32_bf16 v[40:43], v[68:71], v[220:223], v[40:43]
	v_mfma_f32_16x16x32_bf16 v[28:31], v[60:63], v[232:235], v[28:31]
	v_mfma_f32_16x16x32_bf16 v[24:27], v[68:71], v[232:235], v[24:27]
	v_mfma_f32_16x16x32_bf16 v[12:15], v[60:63], v[240:243], v[12:15]
	v_mfma_f32_16x16x32_bf16 v[8:11], v[68:71], v[240:243], v[8:11]
	v_mfma_f32_16x16x32_bf16 v[48:51], v[182:185], v[208:211], v[48:51]
	v_mfma_f32_16x16x32_bf16 v[68:71], v[186:189], v[212:215], v[48:51]
	v_mfma_f32_16x16x32_bf16 v[48:51], v[200:203], v[208:211], v[52:55]
	v_mfma_f32_16x16x32_bf16 v[36:39], v[182:185], v[216:219], v[36:39]
	v_mfma_f32_16x16x32_bf16 v[32:35], v[200:203], v[216:219], v[32:35]
	v_mfma_f32_16x16x32_bf16 v[20:23], v[182:185], v[228:231], v[20:23]
	v_mfma_f32_16x16x32_bf16 v[16:19], v[200:203], v[228:231], v[16:19]
	v_mfma_f32_16x16x32_bf16 v[4:7], v[182:185], v[236:239], v[4:7]
	v_mfma_f32_16x16x32_bf16 v[0:3], v[200:203], v[236:239], v[0:3]
	v_mfma_f32_16x16x32_bf16 v[64:67], v[204:207], v[212:215], v[48:51]
	v_mfma_f32_16x16x32_bf16 v[36:39], v[186:189], v[220:223], v[36:39]
	v_mfma_f32_16x16x32_bf16 v[32:35], v[204:207], v[220:223], v[32:35]
	v_mfma_f32_16x16x32_bf16 v[20:23], v[186:189], v[232:235], v[20:23]
	v_mfma_f32_16x16x32_bf16 v[16:19], v[204:207], v[232:235], v[16:19]
	v_mfma_f32_16x16x32_bf16 v[4:7], v[186:189], v[240:243], v[4:7]
	v_mfma_f32_16x16x32_bf16 v[0:3], v[204:207], v[240:243], v[0:3]
	s_barrier
	s_add_i32 s47, s47, 2
	s_add_u32 s0, s0, 0x100
	s_addc_u32 s1, s1, 0
	s_add_u32 s31, s31, 0x100
	s_addc_u32 s46, s46, 0
	s_cmp_gt_u32 s47, 13
	s_cbranch_scc0 .LBB0_104
	s_and_b64 vcc, exec, s[24:25]
	s_cbranch_vccz .LBB0_107
	s_barrier

; #define PG8_STAGE(bufoff, gbase, voff) do { _Pragma("unroll") for (int _i = 0; _i < 2; ++_i) \
;         __builtin_amdgcn_global_load_lds((const unsigned*)((const char*)(gbase) + (voff)[_i]), (LAS unsigned*)(lds + (bufoff) + ldsw + _i * 8192), 16, 0, 0); } while (0)
; #define PG8_LDA(dst, b, h) do { _Pragma("unroll") for (int m = 0; m < 4; ++m) _Pragma("unroll") for (int k = 0; k < 2; ++k) dst[m][k] = *(const LAS bf16x8*)(lds + PG8_SA(b, h) + aoff + m * 2048 + k * 1024); } while (0)
; #define PG8_LDB(dst, b, h) do { _Pragma("unroll") for (int n = 0; n < 2; ++n) _Pragma("unroll") for (int k = 0; k < 2; ++k) dst[n][k] = *(const LAS bf16x8*)(lds + PG8_SB(b, h) + boff + n * 2048 + k * 1024); } while (0)
; #define PG8_MMA(ai, bj, At, Bt) do { __builtin_amdgcn_s_setprio(1); _Pragma("unroll") for (int m = 0; m < 4; ++m) _Pragma("unroll") for (int n = 0; n < 2; ++n) _Pragma("unroll") for (int k = 0; k < 2; ++k) \
;         acc[ai][bj][m][n] = __builtin_amdgcn_mfma_f32_16x16x32_bf16(Bt[n][k], At[m][k], acc[ai][bj][m][n], 0, 0, 0); __builtin_amdgcn_s_setprio(0); } while (0)
; #define PG8_WAIT_V(n) asm volatile("s_waitcnt vmcnt(" #n ")" ::: "memory")
; #define PG8_WAIT_L(n) asm volatile("s_waitcnt lgkmcnt(" #n ")" ::: "memory")
; #define PG8_BAR __builtin_amdgcn_s_barrier()
; #define PG8_SCHED __builtin_amdgcn_sched_barrier(0)
; template <class Epi, class Sched, bool ALIGN_EPI>
; DI void gemm_phase(LAS unsigned char* lds, const Gemm g, const Sched& S, const Epi& E) {
;     ...
;             const bool last = (t == nt - 2);
;             const char* a1 = cA + (size_t)(t + 1) * kstep;
;             const char* a2 = last ? nA : cA + (size_t)(t + 2) * kstep; const char* b2 = last ? nB : cB + (size_t)(t + 2) * kstep;
;             const char* a3 = a2 + kstep; const char* b3 = b2 + kstep;
;             PG8_LDB(B0, 0, 0); PG8_LDB(B1, 0, 1); PG8_SCHED; PG8_LDA(At, 0, 0); PG8_STAGE(PG8_SA(1, 1), a1 + hstep, voffA);
;             PG8_WAIT_V(8); PG8_WAIT_L(0); PG8_BAR; PG8_MMA(0, 0, At, B0); PG8_MMA(0, 1, At, B1); PG8_BAR; PG8_SCHED;
;             PG8_LDA(At, 0, 1); PG8_STAGE(PG8_SB(0, 0), b2, voffA); PG8_STAGE(PG8_SB(0, 1), b2 + hstep, voffA); PG8_STAGE(PG8_SA(0, 0), a2, voffA);
;             PG8_WAIT_V(8); PG8_WAIT_L(0); PG8_BAR; PG8_MMA(1, 0, At, B0); PG8_MMA(1, 1, At, B1); PG8_BAR; PG8_SCHED;
.LBB0_791:
	s_add_u32 s16, s0, 0xfff50080
	s_addc_u32 s17, s1, -1
	s_add_i32 s42, 0, 0x10000
	s_cmp_eq_u32 s37, 40
	s_cselect_b32 s19, s13, s17
	s_cselect_b32 s18, s12, s16
	s_cselect_b32 s17, s5, s36
	s_cselect_b32 s16, s4, s35
	s_add_i32 s44, 0, 0x14000
	v_add_u32_e32 v140, s42, v165
	v_add_u32_e32 v156, s44, v165
	ds_read_b128 v[128:131], v140
	ds_read_b128 v[132:135], v140 offset:1024
	ds_read_b128 v[136:139], v140 offset:2048
	ds_read_b128 v[140:143], v140 offset:3072
	ds_read_b128 v[144:147], v156
	ds_read_b128 v[148:151], v156 offset:1024
	ds_read_b128 v[152:155], v156 offset:2048
	ds_read_b128 v[156:159], v156 offset:3072
	s_add_i32 m0, s23, 0xc000
	ds_read_b128 v[160:163], v167
	ds_read_b128 v[182:185], v167 offset:1024
	ds_read_b128 v[186:189], v167 offset:2048
	ds_read_b128 v[190:193], v167 offset:3072
	ds_read_b128 v[194:197], v167 offset:4096
	ds_read_b128 v[198:201], v167 offset:5120
	ds_read_b128 v[202:205], v167 offset:6144
	ds_read_b128 v[206:209], v167 offset:7168
	global_load_lds_dwordx4 v170, s[0:1]
	s_add_i32 m0, s23, 0xe000
	s_nop 0
	global_load_lds_dwordx4 v168, s[0:1]
	s_waitcnt vmcnt(8)
	s_waitcnt lgkmcnt(0)
	s_barrier
	v_mfma_f32_16x16x32_bf16 v[124:127], v[128:131], v[160:163], v[124:127]
	v_mfma_f32_16x16x32_bf16 v[120:123], v[136:139], v[160:163], v[120:123]
	v_mfma_f32_16x16x32_bf16 v[108:111], v[128:131], v[186:189], v[108:111]
	v_mfma_f32_16x16x32_bf16 v[104:107], v[136:139], v[186:189], v[104:107]
	v_mfma_f32_16x16x32_bf16 v[96:99], v[128:131], v[194:197], v[96:99]
	v_mfma_f32_16x16x32_bf16 v[88:91], v[136:139], v[194:197], v[88:91]
	v_mfma_f32_16x16x32_bf16 v[80:83], v[128:131], v[202:205], v[80:83]
	v_mfma_f32_16x16x32_bf16 v[72:75], v[136:139], v[202:205], v[72:75]
	v_mfma_f32_16x16x32_bf16 v[124:127], v[132:135], v[182:185], v[124:127]
	v_mfma_f32_16x16x32_bf16 v[120:123], v[140:143], v[182:185], v[120:123]
	v_mfma_f32_16x16x32_bf16 v[108:111], v[132:135], v[190:193], v[108:111]
	v_mfma_f32_16x16x32_bf16 v[104:107], v[140:143], v[190:193], v[104:107]
	v_mfma_f32_16x16x32_bf16 v[96:99], v[132:135], v[198:201], v[96:99]
	v_mfma_f32_16x16x32_bf16 v[88:91], v[140:143], v[198:201], v[88:91]
	v_mfma_f32_16x16x32_bf16 v[80:83], v[132:135], v[206:209], v[80:83]
	v_mfma_f32_16x16x32_bf16 v[72:75], v[140:143], v[206:209], v[72:75]
	v_mfma_f32_16x16x32_bf16 v[116:119], v[144:147], v[160:163], v[116:119]
	v_mfma_f32_16x16x32_bf16 v[112:115], v[152:155], v[160:163], v[112:115]
	v_mfma_f32_16x16x32_bf16 v[100:103], v[144:147], v[186:189], v[100:103]
	v_mfma_f32_16x16x32_bf16 v[92:95], v[152:155], v[186:189], v[92:95]
	v_mfma_f32_16x16x32_bf16 v[84:87], v[144:147], v[194:197], v[84:87]
	v_mfma_f32_16x16x32_bf16 v[76:79], v[152:155], v[194:197], v[76:79]
	v_mfma_f32_16x16x32_bf16 v[68:71], v[144:147], v[202:205], v[68:71]
	v_mfma_f32_16x16x32_bf16 v[64:67], v[152:155], v[202:205], v[64:67]
	v_mfma_f32_16x16x32_bf16 v[116:119], v[148:151], v[182:185], v[116:119]
	v_mfma_f32_16x16x32_bf16 v[112:115], v[156:159], v[182:185], v[112:115]
	v_mfma_f32_16x16x32_bf16 v[100:103], v[148:151], v[190:193], v[100:103]
	v_mfma_f32_16x16x32_bf16 v[92:95], v[156:159], v[190:193], v[92:95]
	v_mfma_f32_16x16x32_bf16 v[84:87], v[148:151], v[198:201], v[84:87]
	v_mfma_f32_16x16x32_bf16 v[76:79], v[156:159], v[198:201], v[76:79]
	v_mfma_f32_16x16x32_bf16 v[68:71], v[148:151], v[206:209], v[68:71]
	v_mfma_f32_16x16x32_bf16 v[64:67], v[156:159], v[206:209], v[64:67]
	s_barrier
	s_add_i32 s42, s42, s20
	s_add_u32 s94, s16, s2
	s_addc_u32 s95, s17, s3
	s_add_u32 s96, s18, s2
	s_addc_u32 s97, s19, s3
	s_mov_b32 m0, s42
	ds_read_b128 v[160:163], v167 offset:16384
	ds_read_b128 v[182:185], v167 offset:17408
	ds_read_b128 v[186:189], v167 offset:18432
	ds_read_b128 v[190:193], v167 offset:19456
	ds_read_b128 v[194:197], v167 offset:20480
	ds_read_b128 v[198:201], v167 offset:21504
	ds_read_b128 v[202:205], v167 offset:22528
	ds_read_b128 v[206:209], v167 offset:23552
	global_load_lds_dwordx4 v170, s[16:17]
	s_add_i32 m0, s42, 0x2000
	s_add_u32 s42, s16, 0xb0000
	s_addc_u32 s43, s17, 0
	s_add_i32 s44, s44, s20
	global_load_lds_dwordx4 v168, s[16:17]
	s_mov_b32 m0, s44
	s_nop 0
	global_load_lds_dwordx4 v170, s[42:43]
	s_add_i32 m0, s44, 0x2000
	s_nop 0
	global_load_lds_dwordx4 v168, s[42:43]
	s_mov_b32 m0, s23
	s_nop 0
	global_load_lds_dwordx4 v170, s[18:19]
	s_mov_b32 m0, s24
	s_nop 0
	global_load_lds_dwordx4 v168, s[18:19]
	s_waitcnt vmcnt(8)
	s_waitcnt lgkmcnt(0)
	s_barrier
	v_mfma_f32_16x16x32_bf16 v[60:63], v[128:131], v[160:163], v[60:63]
	v_mfma_f32_16x16x32_bf16 v[56:59], v[136:139], v[160:163], v[56:59]
	v_mfma_f32_16x16x32_bf16 v[48:51], v[128:131], v[186:189], v[48:51]
	v_mfma_f32_16x16x32_bf16 v[40:43], v[136:139], v[186:189], v[40:43]
	v_mfma_f32_16x16x32_bf16 v[32:35], v[128:131], v[194:197], v[32:35]
	v_mfma_f32_16x16x32_bf16 v[24:27], v[136:139], v[194:197], v[24:27]
	v_mfma_f32_16x16x32_bf16 v[16:19], v[128:131], v[202:205], v[16:19]
	v_mfma_f32_16x16x32_bf16 v[8:11], v[136:139], v[202:205], v[8:11]
	v_mfma_f32_16x16x32_bf16 v[60:63], v[132:135], v[182:185], v[60:63]
	v_mfma_f32_16x16x32_bf16 v[56:59], v[140:143], v[182:185], v[56:59]
	v_mfma_f32_16x16x32_bf16 v[48:51], v[132:135], v[190:193], v[48:51]
	v_mfma_f32_16x16x32_bf16 v[40:43], v[140:143], v[190:193], v[40:43]
	v_mfma_f32_16x16x32_bf16 v[32:35], v[132:135], v[198:201], v[32:35]
	v_mfma_f32_16x16x32_bf16 v[24:27], v[140:143], v[198:201], v[24:27]
	v_mfma_f32_16x16x32_bf16 v[16:19], v[132:135], v[206:209], v[16:19]
	v_mfma_f32_16x16x32_bf16 v[8:11], v[140:143], v[206:209], v[8:11]
	v_mfma_f32_16x16x32_bf16 v[52:55], v[144:147], v[160:163], v[52:55]
	v_mfma_f32_16x16x32_bf16 v[44:47], v[152:155], v[160:163], v[44:47]
	v_mfma_f32_16x16x32_bf16 v[36:39], v[144:147], v[186:189], v[36:39]
	v_mfma_f32_16x16x32_bf16 v[28:31], v[152:155], v[186:189], v[28:31]
	v_mfma_f32_16x16x32_bf16 v[20:23], v[144:147], v[194:197], v[20:23]
	v_mfma_f32_16x16x32_bf16 v[12:15], v[152:155], v[194:197], v[12:15]
	v_mfma_f32_16x16x32_bf16 v[4:7], v[144:147], v[202:205], v[4:7]
	v_mfma_f32_16x16x32_bf16 v[0:3], v[152:155], v[202:205], v[0:3]
	v_mfma_f32_16x16x32_bf16 v[52:55], v[148:151], v[182:185], v[52:55]
	v_mfma_f32_16x16x32_bf16 v[44:47], v[156:159], v[182:185], v[44:47]
	v_mfma_f32_16x16x32_bf16 v[36:39], v[148:151], v[190:193], v[36:39]
	v_mfma_f32_16x16x32_bf16 v[28:31], v[156:159], v[190:193], v[28:31]
	v_mfma_f32_16x16x32_bf16 v[20:23], v[148:151], v[198:201], v[20:23]
	v_mfma_f32_16x16x32_bf16 v[12:15], v[156:159], v[198:201], v[12:15]
	v_mfma_f32_16x16x32_bf16 v[4:7], v[148:151], v[206:209], v[4:7]
	v_mfma_f32_16x16x32_bf16 v[0:3], v[156:159], v[206:209], v[0:3]
	s_barrier
; #define PG8_STAGE(bufoff, gbase, voff) do { _Pragma("unroll") for (int _i = 0; _i < 2; ++_i) \
;         __builtin_amdgcn_global_load_lds((const unsigned*)((const char*)(gbase) + (voff)[_i]), (LAS unsigned*)(lds + (bufoff) + ldsw + _i * 8192), 16, 0, 0); } while (0)
; #define PG8_LDA(dst, b, h) do { _Pragma("unroll") for (int m = 0; m < 4; ++m) _Pragma("unroll") for (int k = 0; k < 2; ++k) dst[m][k] = *(const LAS bf16x8*)(lds + PG8_SA(b, h) + aoff + m * 2048 + k * 1024); } while (0)
; #define PG8_LDB(dst, b, h) do { _Pragma("unroll") for (int n = 0; n < 2; ++n) _Pragma("unroll") for (int k = 0; k < 2; ++k) dst[n][k] = *(const LAS bf16x8*)(lds + PG8_SB(b, h) + boff + n * 2048 + k * 1024); } while (0)
; #define PG8_MMA(ai, bj, At, Bt) do { __builtin_amdgcn_s_setprio(1); _Pragma("unroll") for (int m = 0; m < 4; ++m) _Pragma("unroll") for (int n = 0; n < 2; ++n) _Pragma("unroll") for (int k = 0; k < 2; ++k) \
;         acc[ai][bj][m][n] = __builtin_amdgcn_mfma_f32_16x16x32_bf16(Bt[n][k], At[m][k], acc[ai][bj][m][n], 0, 0, 0); __builtin_amdgcn_s_setprio(0); } while (0)
; #define PG8_WAIT_V(n) asm volatile("s_waitcnt vmcnt(" #n ")" ::: "memory")
; #define PG8_WAIT_L(n) asm volatile("s_waitcnt lgkmcnt(" #n ")" ::: "memory")
; #define PG8_BAR __builtin_amdgcn_s_barrier()
; #define PG8_SCHED __builtin_amdgcn_sched_barrier(0)
; template <class Epi, class Sched, bool ALIGN_EPI>
; DI void gemm_phase(LAS unsigned char* lds, const Gemm g, const Sched& S, const Epi& E) {
;     ...
;             PG8_LDB(B0, 1, 0); PG8_LDB(B1, 1, 1); PG8_SCHED; PG8_LDA(At, 1, 0); PG8_STAGE(PG8_SA(0, 1), a2 + hstep, voffA);
;             PG8_WAIT_V(8); PG8_WAIT_L(0); PG8_BAR; PG8_MMA(0, 0, At, B0); PG8_MMA(0, 1, At, B1); PG8_BAR; PG8_SCHED;
;             PG8_LDA(At, 1, 1); PG8_STAGE(PG8_SB(1, 0), b3, voffA); PG8_STAGE(PG8_SB(1, 1), b3 + hstep, voffA); PG8_STAGE(PG8_SA(1, 0), a3, voffA);
;             PG8_WAIT_V(8); PG8_WAIT_L(0); PG8_BAR; PG8_MMA(1, 0, At, B0); PG8_MMA(1, 1, At, B1); PG8_BAR; PG8_SCHED;
;         }
;         if constexpr (ALIGN_EPI) { if (wr == 0) PG8_BAR; }
	s_add_i32 s42, 0, 0x18000
	s_add_i32 s43, 0, 0x1c000
	v_add_u32_e32 v140, s42, v165
	v_add_u32_e32 v156, s43, v165
	ds_read_b128 v[128:131], v140
	ds_read_b128 v[132:135], v140 offset:1024
	ds_read_b128 v[136:139], v140 offset:2048
	ds_read_b128 v[140:143], v140 offset:3072
	ds_read_b128 v[144:147], v156
	ds_read_b128 v[148:151], v156 offset:1024
	ds_read_b128 v[152:155], v156 offset:2048
	ds_read_b128 v[156:159], v156 offset:3072
	s_add_u32 s18, s18, 0xb0000
	s_addc_u32 s19, s19, 0
	s_mov_b32 m0, s25
	ds_read_b128 v[160:163], v167 offset:32768
	ds_read_b128 v[182:185], v167 offset:33792
	ds_read_b128 v[186:189], v167 offset:34816
	ds_read_b128 v[190:193], v167 offset:35840
	ds_read_b128 v[194:197], v167 offset:36864
	ds_read_b128 v[198:201], v167 offset:37888
	ds_read_b128 v[202:205], v167 offset:38912
	ds_read_b128 v[206:209], v167 offset:39936
	global_load_lds_dwordx4 v170, s[18:19]
	s_mov_b32 m0, s26
	s_nop 0
	global_load_lds_dwordx4 v168, s[18:19]
	s_waitcnt vmcnt(8)
	s_waitcnt lgkmcnt(0)
	s_barrier
	v_mfma_f32_16x16x32_bf16 v[124:127], v[128:131], v[160:163], v[124:127]
	v_mfma_f32_16x16x32_bf16 v[120:123], v[136:139], v[160:163], v[120:123]
	v_mfma_f32_16x16x32_bf16 v[108:111], v[128:131], v[186:189], v[108:111]
	v_mfma_f32_16x16x32_bf16 v[104:107], v[136:139], v[186:189], v[104:107]
	v_mfma_f32_16x16x32_bf16 v[96:99], v[128:131], v[194:197], v[96:99]
	v_mfma_f32_16x16x32_bf16 v[88:91], v[136:139], v[194:197], v[88:91]
	v_mfma_f32_16x16x32_bf16 v[80:83], v[128:131], v[202:205], v[80:83]
	v_mfma_f32_16x16x32_bf16 v[72:75], v[136:139], v[202:205], v[72:75]
	v_mfma_f32_16x16x32_bf16 v[124:127], v[132:135], v[182:185], v[124:127]
	v_mfma_f32_16x16x32_bf16 v[120:123], v[140:143], v[182:185], v[120:123]
	v_mfma_f32_16x16x32_bf16 v[108:111], v[132:135], v[190:193], v[108:111]
	v_mfma_f32_16x16x32_bf16 v[104:107], v[140:143], v[190:193], v[104:107]
	v_mfma_f32_16x16x32_bf16 v[96:99], v[132:135], v[198:201], v[96:99]
	v_mfma_f32_16x16x32_bf16 v[88:91], v[140:143], v[198:201], v[88:91]
	v_mfma_f32_16x16x32_bf16 v[80:83], v[132:135], v[206:209], v[80:83]
	v_mfma_f32_16x16x32_bf16 v[72:75], v[140:143], v[206:209], v[72:75]
	v_mfma_f32_16x16x32_bf16 v[116:119], v[144:147], v[160:163], v[116:119]
	v_mfma_f32_16x16x32_bf16 v[112:115], v[152:155], v[160:163], v[112:115]
	v_mfma_f32_16x16x32_bf16 v[100:103], v[144:147], v[186:189], v[100:103]
	v_mfma_f32_16x16x32_bf16 v[92:95], v[152:155], v[186:189], v[92:95]
	v_mfma_f32_16x16x32_bf16 v[84:87], v[144:147], v[194:197], v[84:87]
	v_mfma_f32_16x16x32_bf16 v[76:79], v[152:155], v[194:197], v[76:79]
	v_mfma_f32_16x16x32_bf16 v[68:71], v[144:147], v[202:205], v[68:71]
	v_mfma_f32_16x16x32_bf16 v[64:67], v[152:155], v[202:205], v[64:67]
	v_mfma_f32_16x16x32_bf16 v[116:119], v[148:151], v[182:185], v[116:119]
	v_mfma_f32_16x16x32_bf16 v[112:115], v[156:159], v[182:185], v[112:115]
	v_mfma_f32_16x16x32_bf16 v[100:103], v[148:151], v[190:193], v[100:103]
	v_mfma_f32_16x16x32_bf16 v[92:95], v[156:159], v[190:193], v[92:95]
	v_mfma_f32_16x16x32_bf16 v[84:87], v[148:151], v[198:201], v[84:87]
	v_mfma_f32_16x16x32_bf16 v[76:79], v[156:159], v[198:201], v[76:79]
	v_mfma_f32_16x16x32_bf16 v[68:71], v[148:151], v[206:209], v[68:71]
	v_mfma_f32_16x16x32_bf16 v[64:67], v[156:159], v[206:209], v[64:67]
	s_barrier
	s_add_i32 s18, s42, s20
	s_mov_b32 m0, s18
	ds_read_b128 v[160:163], v167 offset:49152
	ds_read_b128 v[182:185], v167 offset:50176
	ds_read_b128 v[186:189], v167 offset:51200
	ds_read_b128 v[190:193], v167 offset:52224
	ds_read_b128 v[194:197], v167 offset:53248
	ds_read_b128 v[198:201], v167 offset:54272
	ds_read_b128 v[202:205], v167 offset:55296
	ds_read_b128 v[206:209], v167 offset:56320
	global_load_lds_dwordx4 v170, s[94:95]
	s_add_i32 m0, s18, 0x2000
	s_add_u32 s16, s16, 0xb0080
	s_addc_u32 s17, s17, 0
	s_add_i32 s18, s43, s20
	global_load_lds_dwordx4 v168, s[94:95]
	s_mov_b32 m0, s18
	s_nop 0
	global_load_lds_dwordx4 v170, s[16:17]
	s_add_i32 m0, s18, 0x2000
	s_nop 0
	global_load_lds_dwordx4 v168, s[16:17]
	s_mov_b32 m0, s27
	s_nop 0
	global_load_lds_dwordx4 v170, s[96:97]
	s_mov_b32 m0, s28
	s_nop 0
	global_load_lds_dwordx4 v168, s[96:97]
	s_waitcnt vmcnt(8)
	s_waitcnt lgkmcnt(0)
	s_barrier
	v_mfma_f32_16x16x32_bf16 v[60:63], v[128:131], v[160:163], v[60:63]
	v_mfma_f32_16x16x32_bf16 v[56:59], v[136:139], v[160:163], v[56:59]
	v_mfma_f32_16x16x32_bf16 v[48:51], v[128:131], v[186:189], v[48:51]
	v_mfma_f32_16x16x32_bf16 v[40:43], v[136:139], v[186:189], v[40:43]
	v_mfma_f32_16x16x32_bf16 v[32:35], v[128:131], v[194:197], v[32:35]
	v_mfma_f32_16x16x32_bf16 v[24:27], v[136:139], v[194:197], v[24:27]
	v_mfma_f32_16x16x32_bf16 v[16:19], v[128:131], v[202:205], v[16:19]
	v_mfma_f32_16x16x32_bf16 v[8:11], v[136:139], v[202:205], v[8:11]
	v_mfma_f32_16x16x32_bf16 v[60:63], v[132:135], v[182:185], v[60:63]
	v_mfma_f32_16x16x32_bf16 v[56:59], v[140:143], v[182:185], v[56:59]
	v_mfma_f32_16x16x32_bf16 v[48:51], v[132:135], v[190:193], v[48:51]
	v_mfma_f32_16x16x32_bf16 v[40:43], v[140:143], v[190:193], v[40:43]
	v_mfma_f32_16x16x32_bf16 v[32:35], v[132:135], v[198:201], v[32:35]
	v_mfma_f32_16x16x32_bf16 v[24:27], v[140:143], v[198:201], v[24:27]
	v_mfma_f32_16x16x32_bf16 v[16:19], v[132:135], v[206:209], v[16:19]
	v_mfma_f32_16x16x32_bf16 v[8:11], v[140:143], v[206:209], v[8:11]
	v_mfma_f32_16x16x32_bf16 v[52:55], v[144:147], v[160:163], v[52:55]
	v_mfma_f32_16x16x32_bf16 v[44:47], v[152:155], v[160:163], v[44:47]
	v_mfma_f32_16x16x32_bf16 v[36:39], v[144:147], v[186:189], v[36:39]
	v_mfma_f32_16x16x32_bf16 v[28:31], v[152:155], v[186:189], v[28:31]
	v_mfma_f32_16x16x32_bf16 v[20:23], v[144:147], v[194:197], v[20:23]
	v_mfma_f32_16x16x32_bf16 v[12:15], v[152:155], v[194:197], v[12:15]
	v_mfma_f32_16x16x32_bf16 v[4:7], v[144:147], v[202:205], v[4:7]
	v_mfma_f32_16x16x32_bf16 v[0:3], v[152:155], v[202:205], v[0:3]
	v_mfma_f32_16x16x32_bf16 v[52:55], v[148:151], v[182:185], v[52:55]
	v_mfma_f32_16x16x32_bf16 v[44:47], v[156:159], v[182:185], v[44:47]
	v_mfma_f32_16x16x32_bf16 v[36:39], v[148:151], v[190:193], v[36:39]
	v_mfma_f32_16x16x32_bf16 v[28:31], v[156:159], v[190:193], v[28:31]
	v_mfma_f32_16x16x32_bf16 v[20:23], v[148:151], v[198:201], v[20:23]
	v_mfma_f32_16x16x32_bf16 v[12:15], v[156:159], v[198:201], v[12:15]
	v_mfma_f32_16x16x32_bf16 v[4:7], v[148:151], v[206:209], v[4:7]
	v_mfma_f32_16x16x32_bf16 v[0:3], v[156:159], v[206:209], v[0:3]
	s_barrier
	s_add_i32 s37, s37, 2
	s_add_u32 s0, s0, 0x100
	s_addc_u32 s1, s1, 0
	s_add_u32 s35, s35, 0x100
	s_addc_u32 s36, s36, 0
	s_cmp_gt_u32 s37, 41
	s_cbranch_scc0 .LBB0_791
	s_and_b64 vcc, exec, s[10:11]
	s_cbranch_vccz .LBB0_794
	s_barrier

; #define PG8_STAGE(bufoff, gbase, voff) do { _Pragma("unroll") for (int _i = 0; _i < 2; ++_i) \
;         __builtin_amdgcn_global_load_lds((const unsigned*)((const char*)(gbase) + (voff)[_i]), (LAS unsigned*)(lds + (bufoff) + ldsw + _i * 8192), 16, 0, 0); } while (0)
; #define PG8_LDA(dst, b, h) do { _Pragma("unroll") for (int m = 0; m < 4; ++m) _Pragma("unroll") for (int k = 0; k < 2; ++k) dst[m][k] = *(const LAS bf16x8*)(lds + PG8_SA(b, h) + aoff + m * 2048 + k * 1024); } while (0)
; #define PG8_LDB(dst, b, h) do { _Pragma("unroll") for (int n = 0; n < 2; ++n) _Pragma("unroll") for (int k = 0; k < 2; ++k) dst[n][k] = *(const LAS bf16x8*)(lds + PG8_SB(b, h) + boff + n * 2048 + k * 1024); } while (0)
; #define PG8_MMA(ai, bj, At, Bt) do { __builtin_amdgcn_s_setprio(1); _Pragma("unroll") for (int m = 0; m < 4; ++m) _Pragma("unroll") for (int n = 0; n < 2; ++n) _Pragma("unroll") for (int k = 0; k < 2; ++k) \
;         acc[ai][bj][m][n] = __builtin_amdgcn_mfma_f32_16x16x32_bf16(Bt[n][k], At[m][k], acc[ai][bj][m][n], 0, 0, 0); __builtin_amdgcn_s_setprio(0); } while (0)
; #define PG8_WAIT_V(n) asm volatile("s_waitcnt vmcnt(" #n ")" ::: "memory")
; #define PG8_WAIT_L(n) asm volatile("s_waitcnt lgkmcnt(" #n ")" ::: "memory")
; #define PG8_BAR __builtin_amdgcn_s_barrier()
; #define PG8_SCHED __builtin_amdgcn_sched_barrier(0)
; template <class Epi, class Sched, bool ALIGN_EPI>
; DI void gemm_phase(LAS unsigned char* lds, const Gemm g, const Sched& S, const Epi& E) {
;     ...
;             const char* a1 = cA + (size_t)(t + 1) * kstep;
;             const char* a2 = last ? nA : cA + (size_t)(t + 2) * kstep; const char* b2 = last ? nB : cB + (size_t)(t + 2) * kstep;
;             const char* a3 = a2 + kstep; const char* b3 = b2 + kstep;
;             PG8_LDB(B0, 0, 0); PG8_LDB(B1, 0, 1); PG8_SCHED; PG8_LDA(At, 0, 0); PG8_STAGE(PG8_SA(1, 1), a1 + hstep, voffA);
;             PG8_WAIT_V(8); PG8_WAIT_L(0); PG8_BAR; PG8_MMA(0, 0, At, B0); PG8_MMA(0, 1, At, B1); PG8_BAR; PG8_SCHED;
;             PG8_LDA(At, 0, 1); PG8_STAGE(PG8_SB(0, 0), b2, voffA); PG8_STAGE(PG8_SB(0, 1), b2 + hstep, voffA); PG8_STAGE(PG8_SA(0, 0), a2, voffA);
;             PG8_WAIT_V(8); PG8_WAIT_L(0); PG8_BAR; PG8_MMA(1, 0, At, B0); PG8_MMA(1, 1, At, B1); PG8_BAR; PG8_SCHED;
.LBB0_826:
	s_add_u32 s30, s0, 0xfffc0080
	s_addc_u32 s31, s1, -1
	s_add_i32 s46, 0, 0x10000
	s_cmp_eq_u32 s45, 12
	s_cselect_b32 s35, s25, s31
	s_cselect_b32 s34, s24, s30
	s_cselect_b32 s31, s23, s44
	s_cselect_b32 s30, s29, s43
	s_add_i32 s52, 0, 0x14000
	ds_read_b128 v[44:47], v206
	ds_read_b128 v[48:51], v206 offset:1024
	ds_read_b128 v[52:55], v206 offset:2048
	ds_read_b128 v[56:59], v206 offset:3072
	ds_read_b128 v[124:127], v206 offset:16384
	ds_read_b128 v[128:131], v206 offset:17408
	ds_read_b128 v[132:135], v206 offset:18432
	ds_read_b128 v[136:139], v206 offset:19456
	s_add_i32 m0, s93, 0xc000
	ds_read_b128 v[160:163], v245
	ds_read_b128 v[164:167], v245 offset:1024
	ds_read_b128 v[182:185], v245 offset:2048
	ds_read_b128 v[186:189], v245 offset:3072
	ds_read_b128 v[190:193], v245 offset:4096
	ds_read_b128 v[194:197], v245 offset:5120
	ds_read_b128 v[198:201], v245 offset:6144
	ds_read_b128 v[202:205], v245 offset:7168
	global_load_lds_dwordx4 v178, s[0:1]
	s_add_i32 m0, s93, 0xe000
	s_nop 0
	global_load_lds_dwordx4 v180, s[0:1]
	s_waitcnt vmcnt(8)
	s_waitcnt lgkmcnt(0)
	s_barrier
	v_mfma_f32_16x16x32_bf16 v[156:159], v[44:47], v[160:163], v[156:159]
	v_mfma_f32_16x16x32_bf16 v[76:79], v[52:55], v[160:163], v[76:79]
	v_mfma_f32_16x16x32_bf16 v[148:151], v[44:47], v[182:185], v[148:151]
	v_mfma_f32_16x16x32_bf16 v[68:71], v[52:55], v[182:185], v[68:71]
	v_mfma_f32_16x16x32_bf16 v[140:143], v[44:47], v[190:193], v[140:143]
	v_mfma_f32_16x16x32_bf16 v[60:63], v[52:55], v[190:193], v[60:63]
	v_mfma_f32_16x16x32_bf16 v[116:119], v[44:47], v[198:201], v[116:119]
	v_mfma_f32_16x16x32_bf16 v[36:39], v[52:55], v[198:201], v[36:39]
	v_mfma_f32_16x16x32_bf16 v[156:159], v[48:51], v[164:167], v[156:159]
	v_mfma_f32_16x16x32_bf16 v[76:79], v[56:59], v[164:167], v[76:79]
	v_mfma_f32_16x16x32_bf16 v[148:151], v[48:51], v[186:189], v[148:151]
	v_mfma_f32_16x16x32_bf16 v[68:71], v[56:59], v[186:189], v[68:71]
	v_mfma_f32_16x16x32_bf16 v[140:143], v[48:51], v[194:197], v[140:143]
	v_mfma_f32_16x16x32_bf16 v[60:63], v[56:59], v[194:197], v[60:63]
	v_mfma_f32_16x16x32_bf16 v[116:119], v[48:51], v[202:205], v[116:119]
	v_mfma_f32_16x16x32_bf16 v[36:39], v[56:59], v[202:205], v[36:39]
	v_mfma_f32_16x16x32_bf16 v[152:155], v[124:127], v[160:163], v[152:155]
	v_mfma_f32_16x16x32_bf16 v[72:75], v[132:135], v[160:163], v[72:75]
	v_mfma_f32_16x16x32_bf16 v[144:147], v[124:127], v[182:185], v[144:147]
	v_mfma_f32_16x16x32_bf16 v[64:67], v[132:135], v[182:185], v[64:67]
	v_mfma_f32_16x16x32_bf16 v[120:123], v[124:127], v[190:193], v[120:123]
	v_mfma_f32_16x16x32_bf16 v[40:43], v[132:135], v[190:193], v[40:43]
	v_mfma_f32_16x16x32_bf16 v[112:115], v[124:127], v[198:201], v[112:115]
	v_mfma_f32_16x16x32_bf16 v[32:35], v[132:135], v[198:201], v[32:35]
	v_mfma_f32_16x16x32_bf16 v[152:155], v[128:131], v[164:167], v[152:155]
	v_mfma_f32_16x16x32_bf16 v[72:75], v[136:139], v[164:167], v[72:75]
	v_mfma_f32_16x16x32_bf16 v[144:147], v[128:131], v[186:189], v[144:147]
	v_mfma_f32_16x16x32_bf16 v[64:67], v[136:139], v[186:189], v[64:67]
	v_mfma_f32_16x16x32_bf16 v[120:123], v[128:131], v[194:197], v[120:123]
	v_mfma_f32_16x16x32_bf16 v[40:43], v[136:139], v[194:197], v[40:43]
	v_mfma_f32_16x16x32_bf16 v[112:115], v[128:131], v[202:205], v[112:115]
	v_mfma_f32_16x16x32_bf16 v[32:35], v[136:139], v[202:205], v[32:35]
	s_barrier
	s_add_i32 s46, s46, s92
	s_add_u32 s94, s30, s2
	s_addc_u32 s95, s31, s3
	s_add_u32 s96, s34, s2
	s_addc_u32 s97, s35, s3
	s_mov_b32 m0, s46
	ds_read_b128 v[160:163], v245 offset:16384
	ds_read_b128 v[164:167], v245 offset:17408
	ds_read_b128 v[182:185], v245 offset:18432
	ds_read_b128 v[186:189], v245 offset:19456
	ds_read_b128 v[190:193], v245 offset:20480
	ds_read_b128 v[194:197], v245 offset:21504
	ds_read_b128 v[198:201], v245 offset:22528
	ds_read_b128 v[202:205], v245 offset:23552
	global_load_lds_dwordx4 v174, s[30:31]
	s_add_i32 m0, s46, 0x2000
	s_add_u32 s46, s30, 0x40000
	s_addc_u32 s47, s31, 0
	s_add_i32 s52, s52, s92
	global_load_lds_dwordx4 v176, s[30:31]
	s_mov_b32 m0, s52
	s_nop 0
	global_load_lds_dwordx4 v174, s[46:47]
	s_add_i32 m0, s52, 0x2000
	s_nop 0
	global_load_lds_dwordx4 v176, s[46:47]
	s_mov_b32 m0, s93
	s_nop 0
	global_load_lds_dwordx4 v174, s[34:35]
	s_mov_b32 m0, s86
	s_nop 0
	global_load_lds_dwordx4 v176, s[34:35]
	s_waitcnt vmcnt(8)
	s_waitcnt lgkmcnt(0)
	s_barrier
	v_mfma_f32_16x16x32_bf16 v[108:111], v[44:47], v[160:163], v[108:111]
	v_mfma_f32_16x16x32_bf16 v[28:31], v[52:55], v[160:163], v[28:31]
	v_mfma_f32_16x16x32_bf16 v[100:103], v[44:47], v[182:185], v[100:103]
	v_mfma_f32_16x16x32_bf16 v[20:23], v[52:55], v[182:185], v[20:23]
	v_mfma_f32_16x16x32_bf16 v[92:95], v[44:47], v[190:193], v[92:95]
	v_mfma_f32_16x16x32_bf16 v[12:15], v[52:55], v[190:193], v[12:15]
	v_mfma_f32_16x16x32_bf16 v[4:7], v[52:55], v[198:201], v[4:7]
	v_mfma_f32_16x16x32_bf16 v[108:111], v[48:51], v[164:167], v[108:111]
	v_mfma_f32_16x16x32_bf16 v[28:31], v[56:59], v[164:167], v[28:31]
	v_mfma_f32_16x16x32_bf16 v[100:103], v[48:51], v[186:189], v[100:103]
	v_mfma_f32_16x16x32_bf16 v[20:23], v[56:59], v[186:189], v[20:23]
	v_mfma_f32_16x16x32_bf16 v[92:95], v[48:51], v[194:197], v[92:95]
	v_mfma_f32_16x16x32_bf16 v[12:15], v[56:59], v[194:197], v[12:15]
	v_mfma_f32_16x16x32_bf16 v[44:47], v[44:47], v[198:201], v[84:87]
	v_mfma_f32_16x16x32_bf16 v[4:7], v[56:59], v[202:205], v[4:7]
	v_mfma_f32_16x16x32_bf16 v[44:47], v[48:51], v[202:205], v[44:47]
	v_mfma_f32_16x16x32_bf16 v[24:27], v[132:135], v[160:163], v[24:27]
	v_mfma_f32_16x16x32_bf16 v[16:19], v[132:135], v[182:185], v[16:19]
	v_mfma_f32_16x16x32_bf16 v[8:11], v[132:135], v[190:193], v[8:11]
	v_mfma_f32_16x16x32_bf16 v[80:83], v[124:127], v[198:201], v[80:83]
	v_mfma_f32_16x16x32_bf16 v[0:3], v[132:135], v[198:201], v[0:3]
	v_mfma_f32_16x16x32_bf16 v[48:51], v[124:127], v[160:163], v[104:107]
	v_mfma_f32_16x16x32_bf16 v[24:27], v[136:139], v[164:167], v[24:27]
	v_mfma_f32_16x16x32_bf16 v[52:55], v[124:127], v[182:185], v[96:99]
	v_mfma_f32_16x16x32_bf16 v[16:19], v[136:139], v[186:189], v[16:19]
	v_mfma_f32_16x16x32_bf16 v[56:59], v[124:127], v[190:193], v[88:91]
	v_mfma_f32_16x16x32_bf16 v[8:11], v[136:139], v[194:197], v[8:11]
	v_mfma_f32_16x16x32_bf16 v[80:83], v[128:131], v[202:205], v[80:83]
	v_mfma_f32_16x16x32_bf16 v[0:3], v[136:139], v[202:205], v[0:3]
	v_mfma_f32_16x16x32_bf16 v[48:51], v[128:131], v[164:167], v[48:51]
	v_mfma_f32_16x16x32_bf16 v[52:55], v[128:131], v[186:189], v[52:55]
	v_mfma_f32_16x16x32_bf16 v[56:59], v[128:131], v[194:197], v[56:59]
	s_barrier
; #define PG8_STAGE(bufoff, gbase, voff) do { _Pragma("unroll") for (int _i = 0; _i < 2; ++_i) \
;         __builtin_amdgcn_global_load_lds((const unsigned*)((const char*)(gbase) + (voff)[_i]), (LAS unsigned*)(lds + (bufoff) + ldsw + _i * 8192), 16, 0, 0); } while (0)
; #define PG8_LDA(dst, b, h) do { _Pragma("unroll") for (int m = 0; m < 4; ++m) _Pragma("unroll") for (int k = 0; k < 2; ++k) dst[m][k] = *(const LAS bf16x8*)(lds + PG8_SA(b, h) + aoff + m * 2048 + k * 1024); } while (0)
; #define PG8_LDB(dst, b, h) do { _Pragma("unroll") for (int n = 0; n < 2; ++n) _Pragma("unroll") for (int k = 0; k < 2; ++k) dst[n][k] = *(const LAS bf16x8*)(lds + PG8_SB(b, h) + boff + n * 2048 + k * 1024); } while (0)
; #define PG8_MMA(ai, bj, At, Bt) do { __builtin_amdgcn_s_setprio(1); _Pragma("unroll") for (int m = 0; m < 4; ++m) _Pragma("unroll") for (int n = 0; n < 2; ++n) _Pragma("unroll") for (int k = 0; k < 2; ++k) \
;         acc[ai][bj][m][n] = __builtin_amdgcn_mfma_f32_16x16x32_bf16(Bt[n][k], At[m][k], acc[ai][bj][m][n], 0, 0, 0); __builtin_amdgcn_s_setprio(0); } while (0)
; #define PG8_WAIT_V(n) asm volatile("s_waitcnt vmcnt(" #n ")" ::: "memory")
; #define PG8_WAIT_L(n) asm volatile("s_waitcnt lgkmcnt(" #n ")" ::: "memory")
; #define PG8_BAR __builtin_amdgcn_s_barrier()
; #define PG8_SCHED __builtin_amdgcn_sched_barrier(0)
; template <class Epi, class Sched, bool ALIGN_EPI>
; DI void gemm_phase(LAS unsigned char* lds, const Gemm g, const Sched& S, const Epi& E) {
;     ...
;             PG8_LDB(B0, 1, 0); PG8_LDB(B1, 1, 1); PG8_SCHED; PG8_LDA(At, 1, 0); PG8_STAGE(PG8_SA(0, 1), a2 + hstep, voffA);
;             PG8_WAIT_V(8); PG8_WAIT_L(0); PG8_BAR; PG8_MMA(0, 0, At, B0); PG8_MMA(0, 1, At, B1); PG8_BAR; PG8_SCHED;
;             PG8_LDA(At, 1, 1); PG8_STAGE(PG8_SB(1, 0), b3, voffA); PG8_STAGE(PG8_SB(1, 1), b3 + hstep, voffA); PG8_STAGE(PG8_SA(1, 0), a3, voffA);
;             PG8_WAIT_V(8); PG8_WAIT_L(0); PG8_BAR; PG8_MMA(1, 0, At, B0); PG8_MMA(1, 1, At, B1); PG8_BAR; PG8_SCHED;
;         }
;         if constexpr (ALIGN_EPI) { if (wr == 0) PG8_BAR; }
	s_add_i32 s46, 0, 0x18000
	s_add_i32 s47, 0, 0x1c000
	ds_read_b128 v[84:87], v206 offset:32768
	ds_read_b128 v[88:91], v206 offset:33792
	ds_read_b128 v[96:99], v206 offset:34816
	ds_read_b128 v[104:107], v206 offset:35840
	ds_read_b128 v[124:127], v206 offset:49152
	ds_read_b128 v[128:131], v206 offset:50176
	ds_read_b128 v[132:135], v206 offset:51200
	ds_read_b128 v[136:139], v206 offset:52224
	s_add_u32 s34, s34, 0x40000
	s_addc_u32 s35, s35, 0
	s_mov_b32 m0, s33
	ds_read_b128 v[160:163], v245 offset:32768
	ds_read_b128 v[164:167], v245 offset:33792
	ds_read_b128 v[182:185], v245 offset:34816
	ds_read_b128 v[186:189], v245 offset:35840
	ds_read_b128 v[190:193], v245 offset:36864
	ds_read_b128 v[194:197], v245 offset:37888
	ds_read_b128 v[198:201], v245 offset:38912
	ds_read_b128 v[202:205], v245 offset:39936
	global_load_lds_dwordx4 v174, s[34:35]
	s_mov_b32 m0, s78
	s_nop 0
	global_load_lds_dwordx4 v176, s[34:35]
	s_waitcnt vmcnt(8)
	s_waitcnt lgkmcnt(0)
	s_barrier
	v_mfma_f32_16x16x32_bf16 v[156:159], v[84:87], v[160:163], v[156:159]
	v_mfma_f32_16x16x32_bf16 v[76:79], v[96:99], v[160:163], v[76:79]
	v_mfma_f32_16x16x32_bf16 v[148:151], v[84:87], v[182:185], v[148:151]
	v_mfma_f32_16x16x32_bf16 v[68:71], v[96:99], v[182:185], v[68:71]
	v_mfma_f32_16x16x32_bf16 v[140:143], v[84:87], v[190:193], v[140:143]
	v_mfma_f32_16x16x32_bf16 v[60:63], v[96:99], v[190:193], v[60:63]
	v_mfma_f32_16x16x32_bf16 v[116:119], v[84:87], v[198:201], v[116:119]
	v_mfma_f32_16x16x32_bf16 v[36:39], v[96:99], v[198:201], v[36:39]
	v_mfma_f32_16x16x32_bf16 v[156:159], v[88:91], v[164:167], v[156:159]
	v_mfma_f32_16x16x32_bf16 v[76:79], v[104:107], v[164:167], v[76:79]
	v_mfma_f32_16x16x32_bf16 v[148:151], v[88:91], v[186:189], v[148:151]
	v_mfma_f32_16x16x32_bf16 v[68:71], v[104:107], v[186:189], v[68:71]
	v_mfma_f32_16x16x32_bf16 v[140:143], v[88:91], v[194:197], v[140:143]
	v_mfma_f32_16x16x32_bf16 v[60:63], v[104:107], v[194:197], v[60:63]
	v_mfma_f32_16x16x32_bf16 v[116:119], v[88:91], v[202:205], v[116:119]
	v_mfma_f32_16x16x32_bf16 v[36:39], v[104:107], v[202:205], v[36:39]
	v_mfma_f32_16x16x32_bf16 v[152:155], v[124:127], v[160:163], v[152:155]
	v_mfma_f32_16x16x32_bf16 v[72:75], v[132:135], v[160:163], v[72:75]
	v_mfma_f32_16x16x32_bf16 v[144:147], v[124:127], v[182:185], v[144:147]
	v_mfma_f32_16x16x32_bf16 v[64:67], v[132:135], v[182:185], v[64:67]
	v_mfma_f32_16x16x32_bf16 v[120:123], v[124:127], v[190:193], v[120:123]
	v_mfma_f32_16x16x32_bf16 v[40:43], v[132:135], v[190:193], v[40:43]
	v_mfma_f32_16x16x32_bf16 v[112:115], v[124:127], v[198:201], v[112:115]
	v_mfma_f32_16x16x32_bf16 v[32:35], v[132:135], v[198:201], v[32:35]
	v_mfma_f32_16x16x32_bf16 v[152:155], v[128:131], v[164:167], v[152:155]
	v_mfma_f32_16x16x32_bf16 v[72:75], v[136:139], v[164:167], v[72:75]
	v_mfma_f32_16x16x32_bf16 v[144:147], v[128:131], v[186:189], v[144:147]
	v_mfma_f32_16x16x32_bf16 v[64:67], v[136:139], v[186:189], v[64:67]
	v_mfma_f32_16x16x32_bf16 v[120:123], v[128:131], v[194:197], v[120:123]
	v_mfma_f32_16x16x32_bf16 v[40:43], v[136:139], v[194:197], v[40:43]
	v_mfma_f32_16x16x32_bf16 v[112:115], v[128:131], v[202:205], v[112:115]
	v_mfma_f32_16x16x32_bf16 v[32:35], v[136:139], v[202:205], v[32:35]
	s_barrier
	s_add_i32 s34, s46, s92
	s_mov_b32 m0, s34
	ds_read_b128 v[160:163], v245 offset:49152
	ds_read_b128 v[164:167], v245 offset:50176
	ds_read_b128 v[182:185], v245 offset:51200
	ds_read_b128 v[186:189], v245 offset:52224
	ds_read_b128 v[190:193], v245 offset:53248
	ds_read_b128 v[194:197], v245 offset:54272
	ds_read_b128 v[198:201], v245 offset:55296
	ds_read_b128 v[202:205], v245 offset:56320
	global_load_lds_dwordx4 v174, s[94:95]
	s_add_i32 m0, s34, 0x2000
	s_add_u32 s30, s30, 0x40080
	s_addc_u32 s31, s31, 0
	s_add_i32 s34, s47, s92
	global_load_lds_dwordx4 v176, s[94:95]
	s_mov_b32 m0, s34
	s_nop 0
	global_load_lds_dwordx4 v174, s[30:31]
	s_add_i32 m0, s34, 0x2000
	s_nop 0
	global_load_lds_dwordx4 v176, s[30:31]
	s_mov_b32 m0, s8
	s_nop 0
	global_load_lds_dwordx4 v174, s[96:97]
	s_mov_b32 m0, s9
	s_nop 0
	global_load_lds_dwordx4 v176, s[96:97]
	s_waitcnt vmcnt(8)
	s_waitcnt lgkmcnt(0)
	s_barrier
	v_mfma_f32_16x16x32_bf16 v[108:111], v[84:87], v[160:163], v[108:111]
	v_mfma_f32_16x16x32_bf16 v[28:31], v[96:99], v[160:163], v[28:31]
	v_mfma_f32_16x16x32_bf16 v[100:103], v[84:87], v[182:185], v[100:103]
	v_mfma_f32_16x16x32_bf16 v[20:23], v[96:99], v[182:185], v[20:23]
	v_mfma_f32_16x16x32_bf16 v[92:95], v[84:87], v[190:193], v[92:95]
	v_mfma_f32_16x16x32_bf16 v[12:15], v[96:99], v[190:193], v[12:15]
	v_mfma_f32_16x16x32_bf16 v[44:47], v[84:87], v[198:201], v[44:47]
	v_mfma_f32_16x16x32_bf16 v[4:7], v[96:99], v[198:201], v[4:7]
	v_mfma_f32_16x16x32_bf16 v[108:111], v[88:91], v[164:167], v[108:111]
	v_mfma_f32_16x16x32_bf16 v[28:31], v[104:107], v[164:167], v[28:31]
	v_mfma_f32_16x16x32_bf16 v[100:103], v[88:91], v[186:189], v[100:103]
	v_mfma_f32_16x16x32_bf16 v[20:23], v[104:107], v[186:189], v[20:23]
	v_mfma_f32_16x16x32_bf16 v[92:95], v[88:91], v[194:197], v[92:95]
	v_mfma_f32_16x16x32_bf16 v[12:15], v[104:107], v[194:197], v[12:15]
	v_mfma_f32_16x16x32_bf16 v[84:87], v[88:91], v[202:205], v[44:47]
	v_mfma_f32_16x16x32_bf16 v[4:7], v[104:107], v[202:205], v[4:7]
	v_mfma_f32_16x16x32_bf16 v[44:47], v[124:127], v[160:163], v[48:51]
	v_mfma_f32_16x16x32_bf16 v[104:107], v[128:131], v[164:167], v[44:47]
	v_mfma_f32_16x16x32_bf16 v[44:47], v[124:127], v[182:185], v[52:55]
	v_mfma_f32_16x16x32_bf16 v[96:99], v[128:131], v[186:189], v[44:47]
	v_mfma_f32_16x16x32_bf16 v[44:47], v[124:127], v[190:193], v[56:59]
	v_mfma_f32_16x16x32_bf16 v[24:27], v[132:135], v[160:163], v[24:27]
	v_mfma_f32_16x16x32_bf16 v[16:19], v[132:135], v[182:185], v[16:19]
	v_mfma_f32_16x16x32_bf16 v[88:91], v[128:131], v[194:197], v[44:47]
	v_mfma_f32_16x16x32_bf16 v[8:11], v[132:135], v[190:193], v[8:11]
	v_mfma_f32_16x16x32_bf16 v[44:47], v[124:127], v[198:201], v[80:83]
	v_mfma_f32_16x16x32_bf16 v[0:3], v[132:135], v[198:201], v[0:3]
	v_mfma_f32_16x16x32_bf16 v[24:27], v[136:139], v[164:167], v[24:27]
	v_mfma_f32_16x16x32_bf16 v[16:19], v[136:139], v[186:189], v[16:19]
	v_mfma_f32_16x16x32_bf16 v[8:11], v[136:139], v[194:197], v[8:11]
	v_mfma_f32_16x16x32_bf16 v[80:83], v[128:131], v[202:205], v[44:47]
	v_mfma_f32_16x16x32_bf16 v[0:3], v[136:139], v[202:205], v[0:3]
	s_barrier
	s_add_i32 s45, s45, 2
	s_add_u32 s0, s0, 0x100
	s_addc_u32 s1, s1, 0
	s_add_u32 s43, s43, 0x100
	s_addc_u32 s44, s44, 0
	s_cmp_gt_u32 s45, 13
	s_cbranch_scc0 .LBB0_826
	s_and_b64 vcc, exec, s[18:19]
	s_cbranch_vccz .LBB0_829
	s_barrier

; #define PG8_STAGE(bufoff, gbase, voff) do { _Pragma("unroll") for (int _i = 0; _i < 2; ++_i) \
;         __builtin_amdgcn_global_load_lds((const unsigned*)((const char*)(gbase) + (voff)[_i]), (LAS unsigned*)(lds + (bufoff) + ldsw + _i * 8192), 16, 0, 0); } while (0)
; #define PG8_LDA(dst, b, h) do { _Pragma("unroll") for (int m = 0; m < 4; ++m) _Pragma("unroll") for (int k = 0; k < 2; ++k) dst[m][k] = *(const LAS bf16x8*)(lds + PG8_SA(b, h) + aoff + m * 2048 + k * 1024); } while (0)
; #define PG8_LDB(dst, b, h) do { _Pragma("unroll") for (int n = 0; n < 2; ++n) _Pragma("unroll") for (int k = 0; k < 2; ++k) dst[n][k] = *(const LAS bf16x8*)(lds + PG8_SB(b, h) + boff + n * 2048 + k * 1024); } while (0)
; #define PG8_MMA(ai, bj, At, Bt) do { __builtin_amdgcn_s_setprio(1); _Pragma("unroll") for (int m = 0; m < 4; ++m) _Pragma("unroll") for (int n = 0; n < 2; ++n) _Pragma("unroll") for (int k = 0; k < 2; ++k) \
;         acc[ai][bj][m][n] = __builtin_amdgcn_mfma_f32_16x16x32_bf16(Bt[n][k], At[m][k], acc[ai][bj][m][n], 0, 0, 0); __builtin_amdgcn_s_setprio(0); } while (0)
; #define PG8_WAIT_V(n) asm volatile("s_waitcnt vmcnt(" #n ")" ::: "memory")
; #define PG8_WAIT_L(n) asm volatile("s_waitcnt lgkmcnt(" #n ")" ::: "memory")
; #define PG8_BAR __builtin_amdgcn_s_barrier()
; #define PG8_SCHED __builtin_amdgcn_sched_barrier(0)
; template <class Epi, class Sched, bool ALIGN_EPI>
; DI void gemm_phase(LAS unsigned char* lds, const Gemm g, const Sched& S, const Epi& E) {
;     ...
;             const char* a1 = cA + (size_t)(t + 1) * kstep;
;             const char* a2 = last ? nA : cA + (size_t)(t + 2) * kstep; const char* b2 = last ? nB : cB + (size_t)(t + 2) * kstep;
;             const char* a3 = a2 + kstep; const char* b3 = b2 + kstep;
;             PG8_LDB(B0, 0, 0); PG8_LDB(B1, 0, 1); PG8_SCHED; PG8_LDA(At, 0, 0); PG8_STAGE(PG8_SA(1, 1), a1 + hstep, voffA);
;             PG8_WAIT_V(8); PG8_WAIT_L(0); PG8_BAR; PG8_MMA(0, 0, At, B0); PG8_MMA(0, 1, At, B1); PG8_BAR; PG8_SCHED;
;             PG8_LDA(At, 0, 1); PG8_STAGE(PG8_SB(0, 0), b2, voffA); PG8_STAGE(PG8_SB(0, 1), b2 + hstep, voffA); PG8_STAGE(PG8_SA(0, 0), a2, voffA);
;             PG8_WAIT_V(8); PG8_WAIT_L(0); PG8_BAR; PG8_MMA(1, 0, At, B0); PG8_MMA(1, 1, At, B1); PG8_BAR; PG8_SCHED;
.LBB0_957:
	s_add_u32 s16, s0, 0xfffc0080
	s_addc_u32 s17, s1, -1
	s_add_i32 s43, 0, 0x10000
	s_cmp_eq_u32 s42, 12
	s_cselect_b32 s19, s5, s17
	s_cselect_b32 s18, s34, s16
	s_cselect_b32 s17, s15, s37
	s_cselect_b32 s16, s35, s36
	s_add_i32 s50, 0, 0x14000
	v_add_u32_e32 v144, s43, v133
	v_add_u32_e32 v160, s50, v133
	ds_read_b128 v[128:131], v144
	ds_read_b128 v[136:139], v144 offset:1024
	ds_read_b128 v[140:143], v144 offset:2048
	ds_read_b128 v[144:147], v144 offset:3072
	ds_read_b128 v[148:151], v160
	ds_read_b128 v[152:155], v160 offset:1024
	ds_read_b128 v[156:159], v160 offset:2048
	ds_read_b128 v[160:163], v160 offset:3072
	s_add_i32 m0, s22, 0xc000
	ds_read_b128 v[164:167], v135
	ds_read_b128 v[182:185], v135 offset:1024
	ds_read_b128 v[186:189], v135 offset:2048
	ds_read_b128 v[190:193], v135 offset:3072
	ds_read_b128 v[194:197], v135 offset:4096
	ds_read_b128 v[198:201], v135 offset:5120
	ds_read_b128 v[202:205], v135 offset:6144
	ds_read_b128 v[206:209], v135 offset:7168
	global_load_lds_dwordx4 v178, s[0:1]
	s_add_i32 m0, s22, 0xe000
	s_nop 0
	global_load_lds_dwordx4 v180, s[0:1]
	s_waitcnt vmcnt(8)
	s_waitcnt lgkmcnt(0)
	s_barrier
	v_mfma_f32_16x16x32_bf16 v[124:127], v[128:131], v[164:167], v[124:127]
	v_mfma_f32_16x16x32_bf16 v[120:123], v[140:143], v[164:167], v[120:123]
	v_mfma_f32_16x16x32_bf16 v[108:111], v[128:131], v[186:189], v[108:111]
	v_mfma_f32_16x16x32_bf16 v[104:107], v[140:143], v[186:189], v[104:107]
	v_mfma_f32_16x16x32_bf16 v[92:95], v[128:131], v[194:197], v[92:95]
	v_mfma_f32_16x16x32_bf16 v[88:91], v[140:143], v[194:197], v[88:91]
	v_mfma_f32_16x16x32_bf16 v[76:79], v[128:131], v[202:205], v[76:79]
	v_mfma_f32_16x16x32_bf16 v[72:75], v[140:143], v[202:205], v[72:75]
	v_mfma_f32_16x16x32_bf16 v[124:127], v[136:139], v[182:185], v[124:127]
	v_mfma_f32_16x16x32_bf16 v[120:123], v[144:147], v[182:185], v[120:123]
	v_mfma_f32_16x16x32_bf16 v[108:111], v[136:139], v[190:193], v[108:111]
	v_mfma_f32_16x16x32_bf16 v[104:107], v[144:147], v[190:193], v[104:107]
	v_mfma_f32_16x16x32_bf16 v[92:95], v[136:139], v[198:201], v[92:95]
	v_mfma_f32_16x16x32_bf16 v[88:91], v[144:147], v[198:201], v[88:91]
	v_mfma_f32_16x16x32_bf16 v[76:79], v[136:139], v[206:209], v[76:79]
	v_mfma_f32_16x16x32_bf16 v[72:75], v[144:147], v[206:209], v[72:75]
	v_mfma_f32_16x16x32_bf16 v[116:119], v[148:151], v[164:167], v[116:119]
	v_mfma_f32_16x16x32_bf16 v[112:115], v[156:159], v[164:167], v[112:115]
	v_mfma_f32_16x16x32_bf16 v[100:103], v[148:151], v[186:189], v[100:103]
	v_mfma_f32_16x16x32_bf16 v[96:99], v[156:159], v[186:189], v[96:99]
	v_mfma_f32_16x16x32_bf16 v[84:87], v[148:151], v[194:197], v[84:87]
	v_mfma_f32_16x16x32_bf16 v[80:83], v[156:159], v[194:197], v[80:83]
	v_mfma_f32_16x16x32_bf16 v[68:71], v[148:151], v[202:205], v[68:71]
	v_mfma_f32_16x16x32_bf16 v[64:67], v[156:159], v[202:205], v[64:67]
	v_mfma_f32_16x16x32_bf16 v[116:119], v[152:155], v[182:185], v[116:119]
	v_mfma_f32_16x16x32_bf16 v[112:115], v[160:163], v[182:185], v[112:115]
	v_mfma_f32_16x16x32_bf16 v[100:103], v[152:155], v[190:193], v[100:103]
	v_mfma_f32_16x16x32_bf16 v[96:99], v[160:163], v[190:193], v[96:99]
	v_mfma_f32_16x16x32_bf16 v[84:87], v[152:155], v[198:201], v[84:87]
	v_mfma_f32_16x16x32_bf16 v[80:83], v[160:163], v[198:201], v[80:83]
	v_mfma_f32_16x16x32_bf16 v[68:71], v[152:155], v[206:209], v[68:71]
	v_mfma_f32_16x16x32_bf16 v[64:67], v[160:163], v[206:209], v[64:67]
	s_barrier
	s_add_i32 s43, s43, s20
	s_add_u32 s94, s16, s2
	s_addc_u32 s95, s17, s3
	s_add_u32 s96, s18, s2
	s_addc_u32 s97, s19, s3
	s_mov_b32 m0, s43
	ds_read_b128 v[164:167], v135 offset:16384
	ds_read_b128 v[182:185], v135 offset:17408
	ds_read_b128 v[186:189], v135 offset:18432
	ds_read_b128 v[190:193], v135 offset:19456
	ds_read_b128 v[194:197], v135 offset:20480
	ds_read_b128 v[198:201], v135 offset:21504
	ds_read_b128 v[202:205], v135 offset:22528
	ds_read_b128 v[206:209], v135 offset:23552
	global_load_lds_dwordx4 v174, s[16:17]
	s_add_i32 m0, s43, 0x2000
	s_add_u32 s48, s16, 0x40000
	s_addc_u32 s49, s17, 0
	s_add_i32 s43, s50, s20
	global_load_lds_dwordx4 v176, s[16:17]
	s_mov_b32 m0, s43
	s_nop 0
	global_load_lds_dwordx4 v174, s[48:49]
	s_add_i32 m0, s43, 0x2000
	s_nop 0
	global_load_lds_dwordx4 v176, s[48:49]
	s_mov_b32 m0, s22
	s_nop 0
	global_load_lds_dwordx4 v174, s[18:19]
	s_mov_b32 m0, s23
	s_nop 0
	global_load_lds_dwordx4 v176, s[18:19]
	s_waitcnt vmcnt(8)
	s_waitcnt lgkmcnt(0)
	s_barrier
	v_mfma_f32_16x16x32_bf16 v[60:63], v[128:131], v[164:167], v[60:63]
	v_mfma_f32_16x16x32_bf16 v[56:59], v[140:143], v[164:167], v[56:59]
	v_mfma_f32_16x16x32_bf16 v[44:47], v[128:131], v[186:189], v[44:47]
	v_mfma_f32_16x16x32_bf16 v[40:43], v[140:143], v[186:189], v[40:43]
	v_mfma_f32_16x16x32_bf16 v[28:31], v[128:131], v[194:197], v[28:31]
	v_mfma_f32_16x16x32_bf16 v[24:27], v[140:143], v[194:197], v[24:27]
	v_mfma_f32_16x16x32_bf16 v[12:15], v[128:131], v[202:205], v[12:15]
	v_mfma_f32_16x16x32_bf16 v[8:11], v[140:143], v[202:205], v[8:11]
	v_mfma_f32_16x16x32_bf16 v[60:63], v[136:139], v[182:185], v[60:63]
	v_mfma_f32_16x16x32_bf16 v[56:59], v[144:147], v[182:185], v[56:59]
	v_mfma_f32_16x16x32_bf16 v[44:47], v[136:139], v[190:193], v[44:47]
	v_mfma_f32_16x16x32_bf16 v[40:43], v[144:147], v[190:193], v[40:43]
	v_mfma_f32_16x16x32_bf16 v[28:31], v[136:139], v[198:201], v[28:31]
	v_mfma_f32_16x16x32_bf16 v[24:27], v[144:147], v[198:201], v[24:27]
	v_mfma_f32_16x16x32_bf16 v[12:15], v[136:139], v[206:209], v[12:15]
	v_mfma_f32_16x16x32_bf16 v[8:11], v[144:147], v[206:209], v[8:11]
	v_mfma_f32_16x16x32_bf16 v[52:55], v[148:151], v[164:167], v[52:55]
	v_mfma_f32_16x16x32_bf16 v[48:51], v[156:159], v[164:167], v[48:51]
	v_mfma_f32_16x16x32_bf16 v[36:39], v[148:151], v[186:189], v[36:39]
	v_mfma_f32_16x16x32_bf16 v[32:35], v[156:159], v[186:189], v[32:35]
	v_mfma_f32_16x16x32_bf16 v[20:23], v[148:151], v[194:197], v[20:23]
	v_mfma_f32_16x16x32_bf16 v[16:19], v[156:159], v[194:197], v[16:19]
	v_mfma_f32_16x16x32_bf16 v[4:7], v[148:151], v[202:205], v[4:7]
	v_mfma_f32_16x16x32_bf16 v[0:3], v[156:159], v[202:205], v[0:3]
	v_mfma_f32_16x16x32_bf16 v[52:55], v[152:155], v[182:185], v[52:55]
	v_mfma_f32_16x16x32_bf16 v[48:51], v[160:163], v[182:185], v[48:51]
	v_mfma_f32_16x16x32_bf16 v[36:39], v[152:155], v[190:193], v[36:39]
	v_mfma_f32_16x16x32_bf16 v[32:35], v[160:163], v[190:193], v[32:35]
	v_mfma_f32_16x16x32_bf16 v[20:23], v[152:155], v[198:201], v[20:23]
	v_mfma_f32_16x16x32_bf16 v[16:19], v[160:163], v[198:201], v[16:19]
	v_mfma_f32_16x16x32_bf16 v[4:7], v[152:155], v[206:209], v[4:7]
	v_mfma_f32_16x16x32_bf16 v[0:3], v[160:163], v[206:209], v[0:3]
	s_barrier
; #define PG8_STAGE(bufoff, gbase, voff) do { _Pragma("unroll") for (int _i = 0; _i < 2; ++_i) \
;         __builtin_amdgcn_global_load_lds((const unsigned*)((const char*)(gbase) + (voff)[_i]), (LAS unsigned*)(lds + (bufoff) + ldsw + _i * 8192), 16, 0, 0); } while (0)
; #define PG8_LDA(dst, b, h) do { _Pragma("unroll") for (int m = 0; m < 4; ++m) _Pragma("unroll") for (int k = 0; k < 2; ++k) dst[m][k] = *(const LAS bf16x8*)(lds + PG8_SA(b, h) + aoff + m * 2048 + k * 1024); } while (0)
; #define PG8_LDB(dst, b, h) do { _Pragma("unroll") for (int n = 0; n < 2; ++n) _Pragma("unroll") for (int k = 0; k < 2; ++k) dst[n][k] = *(const LAS bf16x8*)(lds + PG8_SB(b, h) + boff + n * 2048 + k * 1024); } while (0)
; #define PG8_MMA(ai, bj, At, Bt) do { __builtin_amdgcn_s_setprio(1); _Pragma("unroll") for (int m = 0; m < 4; ++m) _Pragma("unroll") for (int n = 0; n < 2; ++n) _Pragma("unroll") for (int k = 0; k < 2; ++k) \
;         acc[ai][bj][m][n] = __builtin_amdgcn_mfma_f32_16x16x32_bf16(Bt[n][k], At[m][k], acc[ai][bj][m][n], 0, 0, 0); __builtin_amdgcn_s_setprio(0); } while (0)
; #define PG8_WAIT_V(n) asm volatile("s_waitcnt vmcnt(" #n ")" ::: "memory")
; #define PG8_WAIT_L(n) asm volatile("s_waitcnt lgkmcnt(" #n ")" ::: "memory")
; #define PG8_BAR __builtin_amdgcn_s_barrier()
; #define PG8_SCHED __builtin_amdgcn_sched_barrier(0)
; template <class Epi, class Sched, bool ALIGN_EPI>
; DI void gemm_phase(LAS unsigned char* lds, const Gemm g, const Sched& S, const Epi& E) {
;     ...
;             PG8_LDB(B0, 1, 0); PG8_LDB(B1, 1, 1); PG8_SCHED; PG8_LDA(At, 1, 0); PG8_STAGE(PG8_SA(0, 1), a2 + hstep, voffA);
;             PG8_WAIT_V(8); PG8_WAIT_L(0); PG8_BAR; PG8_MMA(0, 0, At, B0); PG8_MMA(0, 1, At, B1); PG8_BAR; PG8_SCHED;
;             PG8_LDA(At, 1, 1); PG8_STAGE(PG8_SB(1, 0), b3, voffA); PG8_STAGE(PG8_SB(1, 1), b3 + hstep, voffA); PG8_STAGE(PG8_SA(1, 0), a3, voffA);
;             PG8_WAIT_V(8); PG8_WAIT_L(0); PG8_BAR; PG8_MMA(1, 0, At, B0); PG8_MMA(1, 1, At, B1); PG8_BAR; PG8_SCHED;
;         }
;         if constexpr (ALIGN_EPI) { if (wr == 0) PG8_BAR; }
	s_add_i32 s43, 0, 0x18000
	s_add_i32 s48, 0, 0x1c000
	v_add_u32_e32 v144, s43, v133
	v_add_u32_e32 v160, s48, v133
	ds_read_b128 v[128:131], v144
	ds_read_b128 v[136:139], v144 offset:1024
	ds_read_b128 v[140:143], v144 offset:2048
	ds_read_b128 v[144:147], v144 offset:3072
	ds_read_b128 v[148:151], v160
	ds_read_b128 v[152:155], v160 offset:1024
	ds_read_b128 v[156:159], v160 offset:2048
	ds_read_b128 v[160:163], v160 offset:3072
	s_add_u32 s18, s18, 0x40000
	s_addc_u32 s19, s19, 0
	s_mov_b32 m0, s24
	ds_read_b128 v[164:167], v135 offset:32768
	ds_read_b128 v[182:185], v135 offset:33792
	ds_read_b128 v[186:189], v135 offset:34816
	ds_read_b128 v[190:193], v135 offset:35840
	ds_read_b128 v[194:197], v135 offset:36864
	ds_read_b128 v[198:201], v135 offset:37888
	ds_read_b128 v[202:205], v135 offset:38912
	ds_read_b128 v[206:209], v135 offset:39936
	global_load_lds_dwordx4 v174, s[18:19]
	s_mov_b32 m0, s25
	s_nop 0
	global_load_lds_dwordx4 v176, s[18:19]
	s_waitcnt vmcnt(8)
	s_waitcnt lgkmcnt(0)
	s_barrier
	v_mfma_f32_16x16x32_bf16 v[124:127], v[128:131], v[164:167], v[124:127]
	v_mfma_f32_16x16x32_bf16 v[120:123], v[140:143], v[164:167], v[120:123]
	v_mfma_f32_16x16x32_bf16 v[108:111], v[128:131], v[186:189], v[108:111]
	v_mfma_f32_16x16x32_bf16 v[104:107], v[140:143], v[186:189], v[104:107]
	v_mfma_f32_16x16x32_bf16 v[92:95], v[128:131], v[194:197], v[92:95]
	v_mfma_f32_16x16x32_bf16 v[88:91], v[140:143], v[194:197], v[88:91]
	v_mfma_f32_16x16x32_bf16 v[76:79], v[128:131], v[202:205], v[76:79]
	v_mfma_f32_16x16x32_bf16 v[72:75], v[140:143], v[202:205], v[72:75]
	v_mfma_f32_16x16x32_bf16 v[124:127], v[136:139], v[182:185], v[124:127]
	v_mfma_f32_16x16x32_bf16 v[120:123], v[144:147], v[182:185], v[120:123]
	v_mfma_f32_16x16x32_bf16 v[108:111], v[136:139], v[190:193], v[108:111]
	v_mfma_f32_16x16x32_bf16 v[104:107], v[144:147], v[190:193], v[104:107]
	v_mfma_f32_16x16x32_bf16 v[92:95], v[136:139], v[198:201], v[92:95]
	v_mfma_f32_16x16x32_bf16 v[88:91], v[144:147], v[198:201], v[88:91]
	v_mfma_f32_16x16x32_bf16 v[76:79], v[136:139], v[206:209], v[76:79]
	v_mfma_f32_16x16x32_bf16 v[72:75], v[144:147], v[206:209], v[72:75]
	v_mfma_f32_16x16x32_bf16 v[116:119], v[148:151], v[164:167], v[116:119]
	v_mfma_f32_16x16x32_bf16 v[112:115], v[156:159], v[164:167], v[112:115]
	v_mfma_f32_16x16x32_bf16 v[100:103], v[148:151], v[186:189], v[100:103]
	v_mfma_f32_16x16x32_bf16 v[96:99], v[156:159], v[186:189], v[96:99]
	v_mfma_f32_16x16x32_bf16 v[84:87], v[148:151], v[194:197], v[84:87]
	v_mfma_f32_16x16x32_bf16 v[80:83], v[156:159], v[194:197], v[80:83]
	v_mfma_f32_16x16x32_bf16 v[68:71], v[148:151], v[202:205], v[68:71]
	v_mfma_f32_16x16x32_bf16 v[64:67], v[156:159], v[202:205], v[64:67]
	v_mfma_f32_16x16x32_bf16 v[116:119], v[152:155], v[182:185], v[116:119]
	v_mfma_f32_16x16x32_bf16 v[112:115], v[160:163], v[182:185], v[112:115]
	v_mfma_f32_16x16x32_bf16 v[100:103], v[152:155], v[190:193], v[100:103]
	v_mfma_f32_16x16x32_bf16 v[96:99], v[160:163], v[190:193], v[96:99]
	v_mfma_f32_16x16x32_bf16 v[84:87], v[152:155], v[198:201], v[84:87]
	v_mfma_f32_16x16x32_bf16 v[80:83], v[160:163], v[198:201], v[80:83]
	v_mfma_f32_16x16x32_bf16 v[68:71], v[152:155], v[206:209], v[68:71]
	v_mfma_f32_16x16x32_bf16 v[64:67], v[160:163], v[206:209], v[64:67]
	s_barrier
	s_add_i32 s18, s43, s20
	s_mov_b32 m0, s18
	ds_read_b128 v[164:167], v135 offset:49152
	ds_read_b128 v[182:185], v135 offset:50176
	ds_read_b128 v[186:189], v135 offset:51200
	ds_read_b128 v[190:193], v135 offset:52224
	ds_read_b128 v[194:197], v135 offset:53248
	ds_read_b128 v[198:201], v135 offset:54272
	ds_read_b128 v[202:205], v135 offset:55296
	ds_read_b128 v[206:209], v135 offset:56320
	global_load_lds_dwordx4 v174, s[94:95]
	s_add_i32 m0, s18, 0x2000
	s_add_u32 s16, s16, 0x40080
	s_addc_u32 s17, s17, 0
	s_add_i32 s18, s48, s20
	global_load_lds_dwordx4 v176, s[94:95]
	s_mov_b32 m0, s18
	s_nop 0
	global_load_lds_dwordx4 v174, s[16:17]
	s_add_i32 m0, s18, 0x2000
	s_nop 0
	global_load_lds_dwordx4 v176, s[16:17]
	s_mov_b32 m0, s26
	s_nop 0
	global_load_lds_dwordx4 v174, s[96:97]
	s_mov_b32 m0, s27
	s_nop 0
	global_load_lds_dwordx4 v176, s[96:97]
	s_waitcnt vmcnt(8)
	s_waitcnt lgkmcnt(0)
	s_barrier
	v_mfma_f32_16x16x32_bf16 v[60:63], v[128:131], v[164:167], v[60:63]
	v_mfma_f32_16x16x32_bf16 v[56:59], v[140:143], v[164:167], v[56:59]
	v_mfma_f32_16x16x32_bf16 v[44:47], v[128:131], v[186:189], v[44:47]
	v_mfma_f32_16x16x32_bf16 v[40:43], v[140:143], v[186:189], v[40:43]
	v_mfma_f32_16x16x32_bf16 v[28:31], v[128:131], v[194:197], v[28:31]
	v_mfma_f32_16x16x32_bf16 v[24:27], v[140:143], v[194:197], v[24:27]
	v_mfma_f32_16x16x32_bf16 v[12:15], v[128:131], v[202:205], v[12:15]
	v_mfma_f32_16x16x32_bf16 v[8:11], v[140:143], v[202:205], v[8:11]
	v_mfma_f32_16x16x32_bf16 v[60:63], v[136:139], v[182:185], v[60:63]
	v_mfma_f32_16x16x32_bf16 v[56:59], v[144:147], v[182:185], v[56:59]
	v_mfma_f32_16x16x32_bf16 v[44:47], v[136:139], v[190:193], v[44:47]
	v_mfma_f32_16x16x32_bf16 v[40:43], v[144:147], v[190:193], v[40:43]
	v_mfma_f32_16x16x32_bf16 v[28:31], v[136:139], v[198:201], v[28:31]
	v_mfma_f32_16x16x32_bf16 v[24:27], v[144:147], v[198:201], v[24:27]
	v_mfma_f32_16x16x32_bf16 v[12:15], v[136:139], v[206:209], v[12:15]
	v_mfma_f32_16x16x32_bf16 v[8:11], v[144:147], v[206:209], v[8:11]
	v_mfma_f32_16x16x32_bf16 v[52:55], v[148:151], v[164:167], v[52:55]
	v_mfma_f32_16x16x32_bf16 v[48:51], v[156:159], v[164:167], v[48:51]
	v_mfma_f32_16x16x32_bf16 v[36:39], v[148:151], v[186:189], v[36:39]
	v_mfma_f32_16x16x32_bf16 v[32:35], v[156:159], v[186:189], v[32:35]
	v_mfma_f32_16x16x32_bf16 v[20:23], v[148:151], v[194:197], v[20:23]
	v_mfma_f32_16x16x32_bf16 v[16:19], v[156:159], v[194:197], v[16:19]
	v_mfma_f32_16x16x32_bf16 v[4:7], v[148:151], v[202:205], v[4:7]
	v_mfma_f32_16x16x32_bf16 v[0:3], v[156:159], v[202:205], v[0:3]
	v_mfma_f32_16x16x32_bf16 v[52:55], v[152:155], v[182:185], v[52:55]
	v_mfma_f32_16x16x32_bf16 v[48:51], v[160:163], v[182:185], v[48:51]
	v_mfma_f32_16x16x32_bf16 v[36:39], v[152:155], v[190:193], v[36:39]
	v_mfma_f32_16x16x32_bf16 v[32:35], v[160:163], v[190:193], v[32:35]
	v_mfma_f32_16x16x32_bf16 v[20:23], v[152:155], v[198:201], v[20:23]
	v_mfma_f32_16x16x32_bf16 v[16:19], v[160:163], v[198:201], v[16:19]
	v_mfma_f32_16x16x32_bf16 v[4:7], v[152:155], v[206:209], v[4:7]
	v_mfma_f32_16x16x32_bf16 v[0:3], v[160:163], v[206:209], v[0:3]
	s_barrier
	s_add_i32 s42, s42, 2
	s_add_u32 s0, s0, 0x100
	s_addc_u32 s1, s1, 0
	s_add_u32 s36, s36, 0x100
	s_addc_u32 s37, s37, 0
	s_cmp_gt_u32 s42, 13
	s_cbranch_scc0 .LBB0_957
	s_and_b64 vcc, exec, s[12:13]
	s_cbranch_vccz .LBB0_960
	s_barrier
